# layer-1 weight transposition moved into idle tail of layer-0 GEMM2; causal work balanced across SIMD partner waves; post-phase norm weights hoisted out of row loop
# speedup vs baseline: 1.1440x; 1.0124x over previous
; #define KWS() ((unsigned char*)kload<21>())
; __global__ __launch_bounds__(512, 2) void mega(KArgs ka, int ph_lo, int ph_hi) {
;     extern __shared__ __attribute__((aligned(16))) unsigned char shm[];
;     cg::grid_group grid = cg::this_grid();
; #pragma unroll 1
;     for (int ph = ph_lo; ph < ph_hi; ++ph) {
;         if (ph == 0) {
;             Params q{}; unsigned char* ws = KWS();
;             q.c = KIN(1); q.c_ctx = KIN(3); q.w_ada = KIN(4); q.b_ada = KIN(5); q.w_in = KIN(6); q.w_out = KIN(17);
;             q.MOD = (float*)(ws + OFF_MOD); q.wt_in = (u16*)(ws + OFF_W); q.wt_out = (u16*)(ws + OFF_W + SZ_WTIN1);
;             phase_a(q, shm);
;         } else {
;             const int l = (ph == N_PHASES - 1) ? DEPTH : (ph - 1) / 6, k = (ph == N_PHASES - 1) ? 0 : (ph - 1) % 6;
_Z4mega5KArgsii:
	s_mov_b32 s100, 0
	s_load_dwordx2 s[74:75], s[0:1], 0xb0
	s_waitcnt lgkmcnt(0)
	s_cmp_ge_i32 s74, s75
	s_cbranch_scc1 .LBB0_553
	s_add_u32 s66, s0, 0xb8
	s_addc_u32 s67, s1, 0
	s_cmp_gt_i32 s75, 14
	s_cselect_b64 s[4:5], -1, 0
	s_add_i32 s3, 0, 0x8880
	v_writelane_b32 v254, s4, 0
	v_and_b32_e32 v206, 0x3ff, v0
	v_and_b32_e32 v0, 0x3fffffff, v0
	v_writelane_b32 v254, s5, 1
	v_writelane_b32 v254, s3, 2
	s_add_i32 s3, 0, 0x13800
	v_writelane_b32 v254, s3, 3
	s_add_i32 s3, 0, 0xe000
	v_writelane_b32 v254, s3, 4
	s_add_i32 s3, 0, 0x8800
	v_writelane_b32 v254, s3, 5
	s_add_i32 s3, 0, 0x18d00
	v_writelane_b32 v254, s3, 6
	s_add_i32 s3, 0, 0x18f00
	v_writelane_b32 v254, s3, 7
	s_add_i32 s3, 0, 0x19100
	v_writelane_b32 v254, s3, 8
	s_add_i32 s3, 0, 0x19300
	v_writelane_b32 v254, s3, 9
	s_add_i32 s3, 0, 0x19500
	v_writelane_b32 v254, s3, 10
	v_cmp_eq_u32_e64 s[4:5], 0, v0
	s_load_dword s59, s[0:1], 0xb8
	v_mbcnt_lo_u32_b32 v1, -1, 0
	v_writelane_b32 v254, s4, 11
	v_mbcnt_hi_u32_b32 v208, -1, v1
	v_and_b32_e32 v209, 64, v208
	v_writelane_b32 v254, s5, 12
	v_cmp_eq_u32_e64 s[4:5], 0, v206
	s_mov_b32 s33, 0x2aaaaaab
	v_mov_b32_e32 v149, 0
	v_writelane_b32 v254, s4, 13
	s_movk_i32 s51, 0x6800
	s_mov_b32 s63, 0xbfb8aa3b
	v_writelane_b32 v254, s5, 14
	v_writelane_b32 v254, s2, 15
	v_mov_b32_e32 v207, 0x3727c5ac
	s_mov_b32 s41, 0x800000
	s_movk_i32 s68, 0x41ff
	s_movk_i32 s62, 0x9ff
	s_movk_i32 s40, 0x287f
	s_movk_i32 s69, 0x1000
	s_movk_i32 s92, 0x1400
	s_movk_i32 s76, 0x80
	s_mov_b32 s61, 0x3f317217
	s_mov_b32 s64, 0x7f800000
	s_movk_i32 s65, 0x6000
	s_movk_i32 s60, 0x2800
	v_add_u32_e32 v210, 64, v209
	v_xor_b32_e32 v211, 32, v208
	v_xor_b32_e32 v212, 16, v208
	v_xor_b32_e32 v213, 8, v208
	v_xor_b32_e32 v214, 4, v208
	v_xor_b32_e32 v215, 2, v208
	v_xor_b32_e32 v216, 1, v208
	v_mov_b32_e32 v217, 0x7f
	v_mov_b32_e32 v218, 0x41b17218
	v_mov_b32_e32 v219, 0x1fff
	v_mov_b32_e32 v220, 0xff
	v_mov_b32_e32 v221, 1
	v_mov_b64_e32 v[154:155], 0xda9
	v_mov_b64_e32 v[156:157], 0xdaa
	v_mov_b32_e32 v222, 0x3000000
	s_mov_b32 s3, s74
	s_mov_b64 s[46:47], 0x80
	s_mov_b32 s50, 0x3fb504f3
	s_mov_b32 s36, 0
	v_writelane_b32 v254, s66, 16
	s_nop 1
	v_writelane_b32 v254, s67, 17
	s_branch .LBB0_5

; #define KWS() ((unsigned char*)kload<21>())
; #define TIDX tid_()
; #define BIDX bid_()
; #define GDIM gdim_()
; __device__ __forceinline__ float bflo(unsigned w) { return __uint_as_float(w << 16); }
; __device__ __forceinline__ float bfhi(unsigned w) { return __uint_as_float(w & 0xFFFF0000u); }
; __device__ __forceinline__ float siluf(float v) { return v * __builtin_amdgcn_rcpf(1.f + __expf(-v)); }
; __device__ void phase_post(const Params& p, int l) {
;     const int wid = TIDX >> 6, lane = TIDX & 63;
;     const int nw = GDIM * 8;
;     const int c0 = lane * 32;
;     for (int row = BIDX * 8 + wid; row < MROWS; row += nw) {
;         u16* pr = p.P + (size_t)row * PW;
;         {
;             float tv[32]; float ss = 0.f;
; #pragma unroll
;             for (int q = 0; q < 4; ++q) { const u32x4 yv = *(const u32x4*)(pr + 8192 + c0 + q * 8), zv = *(const u32x4*)(pr + 11264 + c0 + q * 8), yb = *(const u32x4*)(p.YB + (size_t)row * 2048 + c0 + q * 8);
; #pragma unroll
;                 for (int e = 0; e < 4; ++e) { const float t0 = (bflo(yv[e]) + bflo(yb[e])) * siluf(bflo(zv[e])), t1 = (bfhi(yv[e]) + bfhi(yb[e])) * siluf(bfhi(zv[e]));
;                     tv[q * 8 + 2 * e] = t0; tv[q * 8 + 2 * e + 1] = t1; ss += t0 * t0 + t1 * t1; } }
;             const float rstd = rsqrtf(wsum(ss) * (1.f / 2048.f) + LN_EPS);
;             const float* sw = p.ssm_w + (size_t)l * 2048 + c0;
; #pragma unroll
;             for (int q = 0; q < 4; ++q) { const f32x4 wa = *(const f32x4*)(sw + q * 8), wb = *(const f32x4*)(sw + q * 8 + 4);
; __global__ __launch_bounds__(512, 2) void mega(KArgs ka, int ph_lo, int ph_hi) {
;     ...
;             } else if (k == 4) {
;                 Params q{}; unsigned char* ws = KWS();
;                 q.mh_w = KIN(10); q.ssm_w = KIN(16); q.P = (u16*)(ws + OFF_P);
;                 q.HB = (u16*)(ws + OFF_U); q.YB = (u16*)(ws + OFF_W + (size_t)((l + 1) & 1) * SZ_WL);
;                 phase_post(q, l);
.LBB0_5:
	s_cmp_lg_u32 s3, 0
	s_mov_b64 s[4:5], -1
	v_writelane_b32 v254, s3, 18
	s_cbranch_scc0 .LBB0_438
	v_readlane_b32 s3, v254, 18
	s_add_i32 s5, s3, -1
	s_mul_hi_i32 s3, s5, 0x2aaaaaab
	s_lshr_b32 s4, s3, 31
	s_add_i32 s6, s3, s4
	s_mov_b32 s4, s6
	v_writelane_b32 v254, s4, 19
	s_mul_i32 s3, s6, 6
	s_sub_i32 s70, s5, s3
	v_writelane_b32 v254, s5, 20
	v_writelane_b32 v254, s5, 21
	s_mov_b64 s[4:5], -1
	s_mov_b64 s[56:57], 0
	s_cmp_lt_i32 s70, 2
	s_mov_b64 s[72:73], 0
	s_cbranch_scc1 .LBB0_290
	s_cmp_gt_i32 s70, 2
	s_cbranch_scc0 .LBB0_254
	s_cmp_gt_i32 s70, 3
	v_writelane_b32 v254, s70, 22
	s_cbranch_scc0 .LBB0_15
	s_cmp_eq_u32 s70, 4
	s_cbranch_scc0 .LBB0_14
	s_load_dwordx2 s[4:5], s[0:1], 0xa8
	s_waitcnt lgkmcnt(0)
	s_load_dwordx2 s[10:11], s[0:1], 0x50
	s_waitcnt lgkmcnt(0)
	s_waitcnt vmcnt(0)
	v_mov_b32_e32 v0, v206
	s_load_dwordx2 s[12:13], s[0:1], 0x80
	s_waitcnt lgkmcnt(0)
	s_waitcnt lgkmcnt(0)
	s_mov_b32 s3, s59
	v_ashrrev_i32_e32 v1, 6, v0
	v_mov_b32_e32 v0, v206
	s_mov_b32 s6, s2
	s_movk_i32 s2, 0x4200
	v_lshl_add_u32 v32, s6, 3, v1
	v_cmp_gt_i32_e32 vcc, s2, v32
	s_and_saveexec_b64 s[6:7], vcc
	s_mov_b64 s[18:19], 0x23d30000
	s_cbranch_execz .LBB0_13
	v_cmp_lt_i32_e32 vcc, v211, v210
	v_readlane_b32 s14, v254, 19
	v_readlane_b32 s15, v254, 20
	v_cndmask_b32_e32 v1, v208, v211, vcc
	v_cmp_lt_i32_e32 vcc, v212, v210
	v_lshlrev_b32_e32 v112, 2, v1
	s_ashr_i32 s15, s14, 31
	v_cndmask_b32_e32 v1, v208, v212, vcc
	v_cmp_lt_i32_e32 vcc, v213, v210
	v_lshlrev_b32_e32 v113, 2, v1
	s_lshl_b32 s8, s3, 3
	v_cndmask_b32_e32 v1, v208, v213, vcc
	v_cmp_lt_i32_e32 vcc, v214, v210
	s_andn2_b32 s9, 1, s14
	v_lshlrev_b32_e32 v114, 2, v1
	v_cndmask_b32_e32 v1, v208, v214, vcc
	v_cmp_lt_i32_e32 vcc, v215, v210
	s_mov_b32 s2, s14
	s_lshl_b64 s[14:15], s[14:15], 13
	v_lshlrev_b32_e32 v115, 2, v1
	v_cndmask_b32_e32 v1, v208, v215, vcc
	v_cmp_lt_i32_e32 vcc, v216, v210
	s_add_u32 s12, s12, s14
	v_lshlrev_b32_e32 v116, 2, v1
	v_cndmask_b32_e32 v1, v208, v216, vcc
	s_addc_u32 s13, s13, s15
	v_lshlrev_b32_e32 v117, 2, v1
	v_lshlrev_b32_e32 v1, 7, v0
	s_add_u32 s10, s10, s14
	s_mul_i32 s16, s9, 0x4500000
	v_and_b32_e32 v148, 0x1f80, v1
	s_addc_u32 s11, s11, s15
	v_and_b32_e32 v0, 63, v0
	s_ashr_i32 s9, s8, 31
	v_lshl_add_u64 v[34:35], s[12:13], 0, v[148:149]
	v_lshl_add_u64 v[36:37], s[10:11], 0, v[148:149]
	v_lshlrev_b32_e32 v148, 6, v0
	v_ashrrev_i32_e32 v33, 31, v32
	v_mov_b64_e32 v[0:1], s[4:5]
	s_add_u32 s12, s4, s16
	v_mad_i64_i32 v[38:39], s[10:11], v32, s51, v[0:1]
	v_lshlrev_b64 v[0:1], 12, v[32:33]
	s_addc_u32 s13, s5, 0
	v_writelane_b32 v254, s2, 19
	s_mul_i32 s10, s3, 0x34000
	s_mul_hi_i32 s11, s8, 0x6800
	v_lshl_add_u64 v[40:41], s[12:13], 0, v[0:1]
	s_lshl_b64 s[12:13], s[8:9], 12
	v_lshl_add_u64 v[42:43], s[4:5], 0, v[0:1]
	s_mov_b64 s[14:15], 0
	v_writelane_b32 v254, s3, 20
	global_load_dwordx4 v[160:163], v[34:35], off
	global_load_dwordx4 v[164:167], v[34:35], off offset:16
	global_load_dwordx4 v[168:171], v[34:35], off offset:32
	global_load_dwordx4 v[172:175], v[34:35], off offset:48
	global_load_dwordx4 v[176:179], v[34:35], off offset:64
	global_load_dwordx4 v[180:183], v[34:35], off offset:80
	global_load_dwordx4 v[184:187], v[34:35], off offset:96
	global_load_dwordx4 v[188:191], v[34:35], off offset:112
	global_load_dwordx4 v[192:195], v[36:37], off
	global_load_dwordx4 v[196:199], v[36:37], off offset:16
	global_load_dwordx4 v[200:203], v[36:37], off offset:32
	global_load_dwordx4 v[224:227], v[36:37], off offset:48
	global_load_dwordx4 v[228:231], v[36:37], off offset:64
	global_load_dwordx4 v[232:235], v[36:37], off offset:80
	global_load_dwordx4 v[236:239], v[36:37], off offset:96
	global_load_dwordx4 v[240:243], v[36:37], off offset:112
	s_waitcnt vmcnt(0)
.LBB0_12:
	v_lshl_add_u64 v[46:47], v[38:39], 0, v[148:149]
	v_add_co_u32_e32 v44, vcc, 0x8a04000, v46
	s_mov_b64 s[4:5], 0x8a04000
	s_nop 0
	v_addc_co_u32_e32 v45, vcc, 0, v47, vcc
	s_mov_b32 s3, 0x8a05000
	v_lshl_add_u64 v[4:5], v[46:47], 0, s[4:5]
	s_mov_b64 s[4:5], 0x8a05800
	v_add_co_u32_e32 v48, vcc, s3, v46
	v_lshl_add_u64 v[6:7], v[46:47], 0, s[4:5]
	v_lshl_add_u64 v[8:9], v[40:41], 0, v[148:149]
	v_addc_co_u32_e32 v49, vcc, 0, v47, vcc
	global_load_dwordx4 v[58:61], v[44:45], off
	global_load_dwordx4 v[0:3], v[4:5], off offset:48
	global_load_dwordx4 v[20:23], v[4:5], off offset:32
	global_load_dwordx4 v[66:69], v[4:5], off offset:16
	global_load_dwordx4 v[70:73], v[48:49], off offset:2048
	global_load_dwordx4 v[12:15], v[6:7], off offset:48
	global_load_dwordx4 v[28:31], v[6:7], off offset:32
	global_load_dwordx4 v[74:77], v[6:7], off offset:16
	s_nop 0
	global_load_dwordx4 v[4:7], v[8:9], off offset:48
	global_load_dwordx4 v[24:27], v[8:9], off offset:32
	global_load_dwordx4 v[78:81], v[8:9], off offset:16
	global_load_dwordx4 v[82:85], v[8:9], off
	s_nop 0
	s_mov_b32 s3, 0x8a00000
	s_mov_b64 s[4:5], 0x8a00000
	v_add_u32_e32 v32, s8, v32
	v_lshl_add_u64 v[38:39], v[38:39], 0, s[10:11]
	v_lshl_add_u64 v[40:41], v[40:41], 0, s[12:13]
	v_mov_b64_e32 v[8:9], v[164:165]
	v_mov_b64_e32 v[10:11], v[166:167]
	v_mov_b64_e32 v[16:17], v[160:161]
	v_mov_b64_e32 v[18:19], v[162:163]
	s_waitcnt vmcnt(7)
	v_lshlrev_b32_e32 v50, 16, v73
	v_mul_f32_e32 v33, 0xbfb8aa3b, v50
	v_exp_f32_e32 v33, v33
	v_and_b32_e32 v51, 0xffff0000, v73
	s_waitcnt vmcnt(3)
	v_lshlrev_b32_e32 v92, 16, v7
	v_lshlrev_b32_e32 v54, 16, v61
	v_add_f32_e32 v33, 1.0, v33
	v_rcp_f32_e32 v52, v33
	v_mul_f32_e32 v33, 0xbfb8aa3b, v51
	v_exp_f32_e32 v33, v33
	v_and_b32_e32 v55, 0xffff0000, v61
	s_waitcnt vmcnt(0)
; __device__ __forceinline__ float bflo(unsigned w) { return __uint_as_float(w << 16); }
; __device__ __forceinline__ float bfhi(unsigned w) { return __uint_as_float(w & 0xFFFF0000u); }
; __device__ __forceinline__ float siluf(float v) { return v * __builtin_amdgcn_rcpf(1.f + __expf(-v)); }
; __device__ void phase_post(const Params& p, int l) {
;     ...
;             for (int q = 0; q < 4; ++q) { const u32x4 yv = *(const u32x4*)(pr + 8192 + c0 + q * 8), zv = *(const u32x4*)(pr + 11264 + c0 + q * 8), yb = *(const u32x4*)(p.YB + (size_t)row * 2048 + c0 + q * 8);
; #pragma unroll
;                 for (int e = 0; e < 4; ++e) { const float t0 = (bflo(yv[e]) + bflo(yb[e])) * siluf(bflo(zv[e])), t1 = (bfhi(yv[e]) + bfhi(yb[e])) * siluf(bfhi(zv[e]));
;                     tv[q * 8 + 2 * e] = t0; tv[q * 8 + 2 * e + 1] = t1; ss += t0 * t0 + t1 * t1; } }
	v_lshlrev_b32_e32 v56, 16, v85
	v_and_b32_e32 v57, 0xffff0000, v85
	v_add_f32_e32 v33, 1.0, v33
	v_rcp_f32_e32 v53, v33
	v_pk_add_f32 v[54:55], v[54:55], v[56:57]
	v_lshlrev_b32_e32 v62, 16, v60
	v_and_b32_e32 v63, 0xffff0000, v60
	v_pk_mul_f32 v[50:51], v[52:53], v[50:51]
	v_lshlrev_b32_e32 v52, 16, v72
	v_mul_f32_e32 v33, 0xbfb8aa3b, v52
	v_exp_f32_e32 v33, v33
	v_and_b32_e32 v53, 0xffff0000, v72
	v_pk_mul_f32 v[50:51], v[54:55], v[50:51]
	v_lshlrev_b32_e32 v60, 16, v84
	v_add_f32_e32 v33, 1.0, v33
	v_rcp_f32_e32 v54, v33
	v_mul_f32_e32 v33, 0xbfb8aa3b, v53
	v_exp_f32_e32 v33, v33
	v_and_b32_e32 v61, 0xffff0000, v84
	v_pk_add_f32 v[60:61], v[62:63], v[60:61]
	v_lshlrev_b32_e32 v64, 16, v59
	v_add_f32_e32 v33, 1.0, v33
	v_rcp_f32_e32 v55, v33
	v_and_b32_e32 v65, 0xffff0000, v59
	v_lshlrev_b32_e32 v72, 16, v83
	v_and_b32_e32 v73, 0xffff0000, v83
	v_pk_mul_f32 v[52:53], v[54:55], v[52:53]
	v_lshlrev_b32_e32 v54, 16, v71
	v_mul_f32_e32 v33, 0xbfb8aa3b, v54
	v_exp_f32_e32 v33, v33
	v_and_b32_e32 v55, 0xffff0000, v71
	v_pk_mul_f32 v[52:53], v[60:61], v[52:53]
	v_pk_add_f32 v[64:65], v[64:65], v[72:73]
	v_add_f32_e32 v33, 1.0, v33
	v_rcp_f32_e32 v60, v33
	v_mul_f32_e32 v33, 0xbfb8aa3b, v55
	v_exp_f32_e32 v33, v33
	v_and_b32_e32 v71, 0xffff0000, v58
	v_and_b32_e32 v59, 0xffff0000, v82
	v_and_b32_e32 v83, 0xffff0000, v69
	v_add_f32_e32 v33, 1.0, v33
	v_rcp_f32_e32 v61, v33
	v_lshlrev_b32_e32 v84, 16, v81
	v_and_b32_e32 v85, 0xffff0000, v81
	v_lshlrev_b32_e32 v86, 16, v79
	v_pk_mul_f32 v[54:55], v[60:61], v[54:55]
	v_lshlrev_b32_e32 v60, 16, v70
	v_mul_f32_e32 v33, 0xbfb8aa3b, v60
	v_exp_f32_e32 v33, v33
	v_and_b32_e32 v61, 0xffff0000, v70
	v_pk_mul_f32 v[54:55], v[64:65], v[54:55]
	v_lshlrev_b32_e32 v70, 16, v58
	v_add_f32_e32 v33, 1.0, v33
	v_rcp_f32_e32 v64, v33
	v_mul_f32_e32 v33, 0xbfb8aa3b, v61
	v_exp_f32_e32 v33, v33
	v_lshlrev_b32_e32 v58, 16, v82
	v_pk_add_f32 v[58:59], v[70:71], v[58:59]
	v_lshlrev_b32_e32 v82, 16, v69
	v_add_f32_e32 v33, 1.0, v33
	v_rcp_f32_e32 v65, v33
	v_pk_add_f32 v[82:83], v[82:83], v[84:85]
	v_lshlrev_b32_e32 v84, 16, v68
	v_and_b32_e32 v85, 0xffff0000, v68
	v_pk_mul_f32 v[60:61], v[64:65], v[60:61]
	v_lshlrev_b32_e32 v68, 16, v80
	v_pk_mul_f32 v[60:61], v[58:59], v[60:61]
	v_lshlrev_b32_e32 v58, 16, v77
	v_mul_f32_e32 v33, 0xbfb8aa3b, v58
	v_exp_f32_e32 v33, v33
	v_and_b32_e32 v59, 0xffff0000, v77
	v_and_b32_e32 v69, 0xffff0000, v80
	v_pk_add_f32 v[68:69], v[84:85], v[68:69]
	v_add_f32_e32 v33, 1.0, v33
	v_rcp_f32_e32 v64, v33
	v_mul_f32_e32 v33, 0xbfb8aa3b, v59
	v_exp_f32_e32 v33, v33
	v_lshlrev_b32_e32 v84, 16, v67
	v_and_b32_e32 v85, 0xffff0000, v67
	v_and_b32_e32 v87, 0xffff0000, v79
	v_add_f32_e32 v33, 1.0, v33
	v_rcp_f32_e32 v65, v33
	v_pk_add_f32 v[84:85], v[84:85], v[86:87]
	v_lshlrev_b32_e32 v86, 16, v66
	v_and_b32_e32 v87, 0xffff0000, v66
	v_pk_mul_f32 v[58:59], v[64:65], v[58:59]
	v_lshlrev_b32_e32 v64, 16, v76
	v_mul_f32_e32 v33, 0xbfb8aa3b, v64
	v_exp_f32_e32 v33, v33
	v_and_b32_e32 v65, 0xffff0000, v76
	v_lshlrev_b32_e32 v66, 16, v78
	v_and_b32_e32 v67, 0xffff0000, v78
	v_add_f32_e32 v33, 1.0, v33
	v_rcp_f32_e32 v76, v33
	v_mul_f32_e32 v33, 0xbfb8aa3b, v65
	v_exp_f32_e32 v33, v33
	v_lshlrev_b32_e32 v78, 16, v31
	v_and_b32_e32 v79, 0xffff0000, v31
	v_pk_add_f32 v[66:67], v[86:87], v[66:67]
	v_add_f32_e32 v33, 1.0, v33
	v_rcp_f32_e32 v77, v33
	v_mul_f32_e32 v31, 0xbfb8aa3b, v78
	v_lshlrev_b32_e32 v86, 16, v23
	v_and_b32_e32 v87, 0xffff0000, v23
	v_pk_mul_f32 v[64:65], v[76:77], v[64:65]
	v_lshlrev_b32_e32 v76, 16, v75
	v_mul_f32_e32 v33, 0xbfb8aa3b, v76
	v_exp_f32_e32 v33, v33
	v_and_b32_e32 v77, 0xffff0000, v75
	v_mul_f32_e32 v23, 0xbfb8aa3b, v79
	v_exp_f32_e32 v31, v31
	v_add_f32_e32 v33, 1.0, v33
	v_rcp_f32_e32 v80, v33
	v_mul_f32_e32 v33, 0xbfb8aa3b, v77
	v_exp_f32_e32 v33, v33
	v_exp_f32_e32 v23, v23
	v_add_f32_e32 v31, 1.0, v31
	v_lshlrev_b32_e32 v88, 16, v27
	v_add_f32_e32 v33, 1.0, v33
	v_rcp_f32_e32 v81, v33
	v_add_f32_e32 v23, 1.0, v23
	v_and_b32_e32 v89, 0xffff0000, v27
	v_pk_add_f32 v[86:87], v[86:87], v[88:89]
	v_pk_mul_f32 v[76:77], v[80:81], v[76:77]
	v_lshlrev_b32_e32 v88, 16, v22
	v_pk_mul_f32 v[76:77], v[84:85], v[76:77]
	v_lshlrev_b32_e32 v84, 16, v74
	v_mul_f32_e32 v33, 0xbfb8aa3b, v84
	v_exp_f32_e32 v33, v33
	v_and_b32_e32 v85, 0xffff0000, v74
	v_and_b32_e32 v89, 0xffff0000, v22
	v_lshlrev_b32_e32 v22, 16, v26
	v_add_f32_e32 v33, 1.0, v33
	v_rcp_f32_e32 v74, v33
	v_mul_f32_e32 v33, 0xbfb8aa3b, v85
	v_exp_f32_e32 v33, v33
	v_lshlrev_b32_e32 v90, 16, v25
	v_and_b32_e32 v91, 0xffff0000, v25
	v_and_b32_e32 v93, 0xffff0000, v7
	v_add_f32_e32 v33, 1.0, v33
	v_rcp_f32_e32 v75, v33
	v_pk_mul_f32 v[72:73], v[54:55], v[54:55]
	v_pk_mul_f32 v[70:71], v[60:61], v[60:61]
	v_pk_mul_f32 v[62:63], v[52:53], v[52:53]
	v_pk_mul_f32 v[74:75], v[74:75], v[84:85]
	v_rcp_f32_e32 v84, v31
	v_rcp_f32_e32 v85, v23
	v_pk_mul_f32 v[56:57], v[50:51], v[50:51]
	v_pk_mul_f32 v[66:67], v[66:67], v[74:75]
	v_pk_mul_f32 v[64:65], v[68:69], v[64:65]
	v_pk_mul_f32 v[78:79], v[84:85], v[78:79]
	v_pk_mul_f32 v[74:75], v[66:67], v[66:67]
	v_pk_mul_f32 v[78:79], v[86:87], v[78:79]
	v_lshlrev_b32_e32 v86, 16, v30
	v_mul_f32_e32 v23, 0xbfb8aa3b, v86
	v_exp_f32_e32 v23, v23
	v_and_b32_e32 v87, 0xffff0000, v30
	v_pk_mul_f32 v[80:81], v[76:77], v[76:77]
	v_pk_mul_f32 v[58:59], v[82:83], v[58:59]
	v_add_f32_e32 v23, 1.0, v23
	v_rcp_f32_e32 v30, v23
	v_and_b32_e32 v23, 0xffff0000, v26
	v_mul_f32_e32 v26, 0xbfb8aa3b, v87
	v_exp_f32_e32 v26, v26
	v_pk_add_f32 v[22:23], v[88:89], v[22:23]
	v_lshlrev_b32_e32 v88, 16, v21
	v_and_b32_e32 v89, 0xffff0000, v21
	v_add_f32_e32 v26, 1.0, v26
	v_rcp_f32_e32 v31, v26
; __device__ __forceinline__ float bflo(unsigned w) { return __uint_as_float(w << 16); }
; __device__ __forceinline__ float bfhi(unsigned w) { return __uint_as_float(w & 0xFFFF0000u); }
; __device__ __forceinline__ float siluf(float v) { return v * __builtin_amdgcn_rcpf(1.f + __expf(-v)); }
; __device__ void phase_post(const Params& p, int l) {
;     ...
;             for (int q = 0; q < 4; ++q) { const u32x4 yv = *(const u32x4*)(pr + 8192 + c0 + q * 8), zv = *(const u32x4*)(pr + 11264 + c0 + q * 8), yb = *(const u32x4*)(p.YB + (size_t)row * 2048 + c0 + q * 8);
; #pragma unroll
;                 for (int e = 0; e < 4; ++e) { const float t0 = (bflo(yv[e]) + bflo(yb[e])) * siluf(bflo(zv[e])), t1 = (bfhi(yv[e]) + bfhi(yb[e])) * siluf(bfhi(zv[e]));
;                     tv[q * 8 + 2 * e] = t0; tv[q * 8 + 2 * e + 1] = t1; ss += t0 * t0 + t1 * t1; } }
;             const float rstd = rsqrtf(wsum(ss) * (1.f / 2048.f) + LN_EPS);
;             const float* sw = p.ssm_w + (size_t)l * 2048 + c0;
	v_pk_add_f32 v[88:89], v[88:89], v[90:91]
	v_lshlrev_b32_e32 v90, 16, v20
	v_and_b32_e32 v91, 0xffff0000, v20
	v_pk_mul_f32 v[26:27], v[30:31], v[86:87]
	v_lshlrev_b32_e32 v30, 16, v29
	v_and_b32_e32 v31, 0xffff0000, v29
	v_mul_f32_e32 v29, 0xbfb8aa3b, v30
	v_mul_f32_e32 v21, 0xbfb8aa3b, v31
	v_exp_f32_e32 v29, v29
	v_exp_f32_e32 v21, v21
	v_lshlrev_b32_e32 v20, 16, v24
	v_pk_mul_f32 v[68:69], v[64:65], v[64:65]
	v_add_f32_e32 v29, 1.0, v29
	v_add_f32_e32 v21, 1.0, v21
	v_rcp_f32_e32 v86, v29
	v_rcp_f32_e32 v87, v21
	v_pk_mul_f32 v[82:83], v[58:59], v[58:59]
	v_pk_mul_f32 v[22:23], v[22:23], v[26:27]
	v_pk_mul_f32 v[84:85], v[78:79], v[78:79]
	v_pk_mul_f32 v[30:31], v[86:87], v[30:31]
	v_pk_mul_f32 v[26:27], v[22:23], v[22:23]
	v_pk_mul_f32 v[30:31], v[88:89], v[30:31]
	v_lshlrev_b32_e32 v88, 16, v28
	v_mul_f32_e32 v21, 0xbfb8aa3b, v88
	v_exp_f32_e32 v21, v21
	v_and_b32_e32 v89, 0xffff0000, v28
	v_pk_mul_f32 v[86:87], v[30:31], v[30:31]
	v_add_f32_e32 v21, 1.0, v21
	v_rcp_f32_e32 v28, v21
	v_and_b32_e32 v21, 0xffff0000, v24
	v_mul_f32_e32 v24, 0xbfb8aa3b, v89
	v_exp_f32_e32 v24, v24
	v_pk_add_f32 v[20:21], v[90:91], v[20:21]
	v_lshlrev_b32_e32 v90, 16, v3
	v_and_b32_e32 v91, 0xffff0000, v3
	v_add_f32_e32 v24, 1.0, v24
	v_rcp_f32_e32 v29, v24
	v_pk_add_f32 v[90:91], v[90:91], v[92:93]
	v_lshlrev_b32_e32 v92, 16, v5
	v_and_b32_e32 v93, 0xffff0000, v5
	v_pk_mul_f32 v[24:25], v[28:29], v[88:89]
	v_lshlrev_b32_e32 v28, 16, v15
	v_and_b32_e32 v29, 0xffff0000, v15
	v_mul_f32_e32 v15, 0xbfb8aa3b, v28
	v_mul_f32_e32 v3, 0xbfb8aa3b, v29
	v_exp_f32_e32 v15, v15
	v_exp_f32_e32 v3, v3
	v_pk_mul_f32 v[20:21], v[20:21], v[24:25]
	v_add_f32_e32 v15, 1.0, v15
	v_add_f32_e32 v3, 1.0, v3
	v_rcp_f32_e32 v88, v15
	v_rcp_f32_e32 v89, v3
	v_pk_mul_f32 v[24:25], v[20:21], v[20:21]
	v_pk_mul_f32 v[28:29], v[88:89], v[28:29]
	v_lshlrev_b32_e32 v88, 16, v14
	v_mul_f32_e32 v3, 0xbfb8aa3b, v88
	v_exp_f32_e32 v3, v3
	v_and_b32_e32 v89, 0xffff0000, v14
	v_pk_mul_f32 v[28:29], v[90:91], v[28:29]
	v_lshlrev_b32_e32 v90, 16, v2
	v_add_f32_e32 v3, 1.0, v3
	v_rcp_f32_e32 v14, v3
	v_and_b32_e32 v91, 0xffff0000, v2
	v_lshlrev_b32_e32 v2, 16, v6
	v_and_b32_e32 v3, 0xffff0000, v6
	v_mul_f32_e32 v6, 0xbfb8aa3b, v89
	v_exp_f32_e32 v6, v6
	v_pk_add_f32 v[2:3], v[90:91], v[2:3]
	v_lshlrev_b32_e32 v90, 16, v1
	v_and_b32_e32 v91, 0xffff0000, v1
	v_add_f32_e32 v6, 1.0, v6
	v_rcp_f32_e32 v15, v6
	v_pk_add_f32 v[90:91], v[90:91], v[92:93]
	v_pk_mul_f32 v[6:7], v[14:15], v[88:89]
	s_nop 0
	v_pk_mul_f32 v[14:15], v[2:3], v[6:7]
	v_mov_b32_e32 v6, v29
	v_mov_b32_e32 v7, v15
	v_mov_b32_e32 v2, v28
	v_mov_b32_e32 v3, v14
	v_pk_mul_f32 v[6:7], v[6:7], v[6:7]
	s_nop 0
	v_pk_fma_f32 v[2:3], v[2:3], v[2:3], v[6:7]
	v_lshlrev_b32_e32 v6, 16, v13
	v_and_b32_e32 v7, 0xffff0000, v13
	v_mul_f32_e32 v13, 0xbfb8aa3b, v6
	v_mul_f32_e32 v1, 0xbfb8aa3b, v7
	v_exp_f32_e32 v13, v13
	v_exp_f32_e32 v1, v1
	v_add_f32_e32 v13, 1.0, v13
	v_add_f32_e32 v1, 1.0, v1
	v_rcp_f32_e32 v88, v13
	v_rcp_f32_e32 v89, v1
	s_nop 0
	v_pk_mul_f32 v[6:7], v[88:89], v[6:7]
	s_nop 0
	v_pk_mul_f32 v[88:89], v[90:91], v[6:7]
	v_lshlrev_b32_e32 v6, 16, v12
	v_mul_f32_e32 v1, 0xbfb8aa3b, v6
	v_exp_f32_e32 v1, v1
	v_and_b32_e32 v7, 0xffff0000, v12
	v_lshlrev_b32_e32 v90, 16, v0
	v_and_b32_e32 v91, 0xffff0000, v0
	v_add_f32_e32 v1, 1.0, v1
	v_rcp_f32_e32 v12, v1
	v_lshlrev_b32_e32 v0, 16, v4
	v_and_b32_e32 v1, 0xffff0000, v4
	v_mul_f32_e32 v4, 0xbfb8aa3b, v7
	v_exp_f32_e32 v4, v4
	v_pk_add_f32 v[0:1], v[90:91], v[0:1]
	v_add_f32_e32 v4, 1.0, v4
	v_rcp_f32_e32 v13, v4
	s_nop 0
	v_pk_mul_f32 v[4:5], v[12:13], v[6:7]
	s_nop 0
	v_pk_mul_f32 v[12:13], v[0:1], v[4:5]
	v_mov_b32_e32 v4, v89
	v_mov_b32_e32 v5, v13
	v_mov_b32_e32 v0, v88
	v_mov_b32_e32 v1, v12
	v_pk_mul_f32 v[4:5], v[4:5], v[4:5]
	s_nop 0
	v_pk_fma_f32 v[0:1], v[0:1], v[0:1], v[4:5]
	v_add_f32_e32 v4, v72, v73
	v_add_f32_e32 v5, v70, v71
	v_add_f32_e32 v4, v5, v4
	v_add_f32_e32 v5, v62, v63
	v_add_f32_e32 v4, v5, v4
	v_add_f32_e32 v5, v56, v57
	v_add_f32_e32 v4, v5, v4
	v_add_f32_e32 v5, v74, v75
	v_add_f32_e32 v4, v4, v5
	v_add_f32_e32 v5, v80, v81
	v_add_f32_e32 v4, v5, v4
	v_add_f32_e32 v5, v68, v69
	v_add_f32_e32 v4, v5, v4
	v_add_f32_e32 v5, v82, v83
	v_add_f32_e32 v4, v5, v4
	v_add_f32_e32 v5, v24, v25
	v_add_f32_e32 v4, v5, v4
	v_add_f32_e32 v5, v86, v87
	v_add_f32_e32 v4, v5, v4
	v_add_f32_e32 v5, v26, v27
	v_add_f32_e32 v4, v5, v4
	v_add_f32_e32 v5, v84, v85
	v_add_f32_e32 v4, v5, v4
	v_add_f32_e32 v1, v1, v4
	v_add_f32_e32 v0, v0, v1
	v_add_f32_e32 v0, v3, v0
	v_add_f32_e32 v0, v2, v0
	ds_bpermute_b32 v1, v112, v0
	s_waitcnt lgkmcnt(0)
	v_add_f32_e32 v0, v0, v1
	ds_bpermute_b32 v1, v113, v0
	s_waitcnt lgkmcnt(0)
	v_add_f32_e32 v0, v0, v1
	ds_bpermute_b32 v1, v114, v0
	s_waitcnt lgkmcnt(0)
	v_add_f32_e32 v0, v0, v1
	ds_bpermute_b32 v1, v115, v0
	s_waitcnt lgkmcnt(0)
	v_add_f32_e32 v0, v0, v1
	ds_bpermute_b32 v1, v116, v0
	s_waitcnt lgkmcnt(0)
	v_add_f32_e32 v0, v0, v1
	ds_bpermute_b32 v1, v117, v0
	s_waitcnt lgkmcnt(0)
	v_add_f32_e32 v0, v0, v1
	v_fmamk_f32 v0, v0, 0x3a000000, v207
	v_cmp_gt_f32_e32 vcc, s41, v0
	v_mul_f32_e32 v1, 0x4b800000, v0
	s_nop 0
	v_cndmask_b32_e32 v0, v0, v1, vcc
	v_rsq_f32_e32 v0, v0
	s_nop 0
	v_mul_f32_e32 v1, 0x45800000, v0
	v_cndmask_b32_e32 v24, v0, v1, vcc
	v_pk_mul_f32 v[0:1], v[60:61], v[24:25] op_sel_hi:[1,0]
	v_pk_mul_f32 v[2:3], v[54:55], v[24:25] op_sel_hi:[1,0]
	s_waitcnt vmcnt(0)
; __device__ __forceinline__ float bflo(unsigned w) { return __uint_as_float(w << 16); }
; __device__ __forceinline__ float bfhi(unsigned w) { return __uint_as_float(w & 0xFFFF0000u); }
; __device__ __forceinline__ unsigned pk2(float lo, float hi) { const f32x2_t v = {lo, hi}; return __builtin_bit_cast(unsigned, __builtin_convertvector(v, bf16x2_t)); }
; __device__ void phase_post(const Params& p, int l) {
;     ...
;             const float* sw = p.ssm_w + (size_t)l * 2048 + c0;
; #pragma unroll
;             for (int q = 0; q < 4; ++q) { const f32x4 wa = *(const f32x4*)(sw + q * 8), wb = *(const f32x4*)(sw + q * 8 + 4);
;                 u32x4 o; o.x = pk2(tv[q * 8] * rstd * wa[0], tv[q * 8 + 1] * rstd * wa[1]); o.y = pk2(tv[q * 8 + 2] * rstd * wa[2], tv[q * 8 + 3] * rstd * wa[3]);
;                 o.z = pk2(tv[q * 8 + 4] * rstd * wb[0], tv[q * 8 + 5] * rstd * wb[1]); o.w = pk2(tv[q * 8 + 6] * rstd * wb[2], tv[q * 8 + 7] * rstd * wb[3]);
;                 *(u32x4*)(pr + 11264 + c0 + q * 8) = o; }
;         }
;         {
;             float hv[32]; float s = 0.f;
; #pragma unroll
;             for (int q = 0; q < 4; ++q) { const u32x4 a = *(const u32x4*)(pr + c0 + q * 8), ab = *(const u32x4*)(p.HB + (size_t)row * 2048 + c0 + q * 8);
; #pragma unroll
;                 for (int e = 0; e < 4; ++e) { const float h0 = bflo(a[e]) + bflo(ab[e]), h1 = bfhi(a[e]) + bfhi(ab[e]); hv[q * 8 + 2 * e] = h0; hv[q * 8 + 2 * e + 1] = h1; s += h0 + h1; } }
	v_pk_mul_f32 v[0:1], v[16:17], v[0:1]
	v_pk_mul_f32 v[2:3], v[18:19], v[2:3]
	v_cvt_pk_bf16_f32 v0, v0, v1
	v_cvt_pk_bf16_f32 v1, v2, v3
	v_pk_mul_f32 v[2:3], v[52:53], v[24:25] op_sel_hi:[1,0]
	v_pk_mul_f32 v[4:5], v[50:51], v[24:25] op_sel_hi:[1,0]
	v_pk_mul_f32 v[2:3], v[8:9], v[2:3]
	v_pk_mul_f32 v[4:5], v[10:11], v[4:5]
	v_cvt_pk_bf16_f32 v2, v2, v3
	v_cvt_pk_bf16_f32 v3, v4, v5
	global_store_dwordx4 v[48:49], v[0:3], off offset:2048
	v_mov_b64_e32 v[4:5], v[168:169]
	v_mov_b64_e32 v[6:7], v[170:171]
	v_mov_b64_e32 v[0:1], v[172:173]
	v_mov_b64_e32 v[2:3], v[174:175]
	v_pk_mul_f32 v[8:9], v[66:67], v[24:25] op_sel_hi:[1,0]
	v_lshl_add_u64 v[10:11], v[42:43], 0, v[148:149]
	v_lshl_add_u64 v[42:43], v[42:43], 0, s[12:13]
	v_pk_mul_f32 v[4:5], v[4:5], v[8:9]
	v_pk_mul_f32 v[8:9], v[76:77], v[24:25] op_sel_hi:[1,0]
	v_cvt_pk_bf16_f32 v4, v4, v5
	v_pk_mul_f32 v[6:7], v[6:7], v[8:9]
	v_pk_mul_f32 v[8:9], v[20:21], v[24:25] op_sel_hi:[1,0]
	v_cvt_pk_bf16_f32 v5, v6, v7
	v_pk_mul_f32 v[6:7], v[64:65], v[24:25] op_sel_hi:[1,0]
	s_nop 0
	v_pk_mul_f32 v[0:1], v[0:1], v[6:7]
	s_nop 0
	v_cvt_pk_bf16_f32 v6, v0, v1
	v_pk_mul_f32 v[0:1], v[58:59], v[24:25] op_sel_hi:[1,0]
	s_nop 0
	v_pk_mul_f32 v[0:1], v[2:3], v[0:1]
	s_nop 0
	v_cvt_pk_bf16_f32 v7, v0, v1
	global_store_dwordx4 v[48:49], v[4:7], off offset:2064
	v_mov_b64_e32 v[0:1], v[180:181]
	v_mov_b64_e32 v[2:3], v[182:183]
	v_mov_b64_e32 v[4:5], v[176:177]
	v_mov_b64_e32 v[6:7], v[178:179]
	v_pk_mul_f32 v[4:5], v[4:5], v[8:9]
	v_pk_mul_f32 v[8:9], v[30:31], v[24:25] op_sel_hi:[1,0]
	v_cvt_pk_bf16_f32 v4, v4, v5
	v_pk_mul_f32 v[6:7], v[6:7], v[8:9]
	v_pk_mul_f32 v[8:9], v[12:13], v[24:25] op_sel_hi:[1,0]
	v_cvt_pk_bf16_f32 v5, v6, v7
	v_pk_mul_f32 v[6:7], v[22:23], v[24:25] op_sel_hi:[1,0]
	s_nop 0
	v_pk_mul_f32 v[0:1], v[0:1], v[6:7]
	s_nop 0
	v_cvt_pk_bf16_f32 v6, v0, v1
	v_pk_mul_f32 v[0:1], v[78:79], v[24:25] op_sel_hi:[1,0]
	s_nop 0
	v_pk_mul_f32 v[0:1], v[2:3], v[0:1]
	s_nop 0
	v_cvt_pk_bf16_f32 v7, v0, v1
	global_store_dwordx4 v[48:49], v[4:7], off offset:2080
	v_mov_b64_e32 v[0:1], v[188:189]
	v_mov_b64_e32 v[2:3], v[190:191]
	v_mov_b64_e32 v[4:5], v[184:185]
	v_mov_b64_e32 v[6:7], v[186:187]
	v_pk_mul_f32 v[4:5], v[4:5], v[8:9]
	v_pk_mul_f32 v[8:9], v[88:89], v[24:25] op_sel_hi:[1,0]
	v_cvt_pk_bf16_f32 v4, v4, v5
	v_pk_mul_f32 v[6:7], v[6:7], v[8:9]
	s_nop 0
	v_cvt_pk_bf16_f32 v5, v6, v7
	v_pk_mul_f32 v[6:7], v[14:15], v[24:25] op_sel_hi:[1,0]
	v_lshl_add_u64 v[14:15], v[10:11], 0, s[18:19]
	v_pk_mul_f32 v[0:1], v[0:1], v[6:7]
	s_nop 0
	v_cvt_pk_bf16_f32 v6, v0, v1
	v_pk_mul_f32 v[0:1], v[28:29], v[24:25] op_sel_hi:[1,0]
	s_nop 0
	v_pk_mul_f32 v[0:1], v[2:3], v[0:1]
	v_add_co_u32_e32 v2, vcc, s3, v46
	v_cvt_pk_bf16_f32 v7, v0, v1
	global_store_dwordx4 v[48:49], v[4:7], off offset:2096
	v_lshl_add_u64 v[0:1], v[46:47], 0, s[4:5]
	v_addc_co_u32_e32 v3, vcc, 0, v47, vcc
	s_mov_b32 s3, 0x23d30000
	global_load_dwordx4 v[84:87], v[2:3], off
	global_load_dwordx4 v[22:25], v[0:1], off offset:48
	s_nop 0
	global_load_dwordx4 v[2:5], v[0:1], off offset:32
	global_load_dwordx4 v[6:9], v[0:1], off offset:16
	v_add_co_u32_e32 v0, vcc, s3, v10
	s_mov_b64 s[4:5], 0x8a02000
	s_nop 0
	v_addc_co_u32_e32 v1, vcc, 0, v11, vcc
	global_load_dwordx4 v[88:91], v[0:1], off
	global_load_dwordx4 v[118:121], v[14:15], off offset:48
	global_load_dwordx4 v[10:13], v[14:15], off offset:32
	s_nop 0
	global_load_dwordx4 v[14:17], v[14:15], off offset:16
	s_mov_b32 s3, 0x8a03000
	s_waitcnt vmcnt(7)
	v_lshlrev_b32_e32 v70, 16, v87
	s_waitcnt vmcnt(6)
	v_lshlrev_b32_e32 v78, 16, v22
	s_waitcnt vmcnt(5)
	v_lshlrev_b32_e32 v56, 16, v2
	s_waitcnt vmcnt(4)
	v_lshlrev_b32_e32 v0, 16, v6
	v_and_b32_e32 v1, 0xffff0000, v6
	v_lshlrev_b32_e32 v94, 16, v7
	v_and_b32_e32 v95, 0xffff0000, v7
	v_and_b32_e32 v57, 0xffff0000, v2
	v_lshlrev_b32_e32 v58, 16, v3
	s_waitcnt vmcnt(0)
	v_lshlrev_b32_e32 v18, 16, v14
	v_and_b32_e32 v19, 0xffff0000, v14
	v_pk_add_f32 v[26:27], v[0:1], v[18:19]
	v_lshlrev_b32_e32 v0, 16, v9
	v_and_b32_e32 v1, 0xffff0000, v9
	v_lshlrev_b32_e32 v6, 16, v17
	v_and_b32_e32 v7, 0xffff0000, v17
	v_pk_add_f32 v[30:31], v[0:1], v[6:7]
	v_lshlrev_b32_e32 v0, 16, v4
	v_pk_add_f32 v[104:105], v[30:31], v[30:31] op_sel_hi:[0,1]
	v_and_b32_e32 v104, 0xffff0000, v3
	v_and_b32_e32 v1, 0xffff0000, v4
	v_lshlrev_b32_e32 v2, 16, v12
	v_and_b32_e32 v3, 0xffff0000, v12
	v_pk_add_f32 v[48:49], v[0:1], v[2:3]
	v_lshlrev_b32_e32 v0, 16, v23
	v_and_b32_e32 v1, 0xffff0000, v23
	v_lshlrev_b32_e32 v2, 16, v119
	v_and_b32_e32 v3, 0xffff0000, v119
	v_pk_add_f32 v[92:93], v[26:27], v[26:27] op_sel_hi:[0,1]
	v_pk_add_f32 v[28:29], v[0:1], v[2:3]
	v_lshl_add_u64 v[0:1], v[46:47], 0, s[4:5]
	s_mov_b64 s[4:5], 0x8a03000
	v_add_co_u32_e32 v2, vcc, s3, v46
	v_lshlrev_b32_e32 v96, 16, v8
	v_and_b32_e32 v92, 0xffff0000, v8
	v_pk_add_f32 v[66:67], v[48:49], v[48:49] op_sel_hi:[0,1]
	v_lshl_add_u64 v[8:9], v[46:47], 0, s[4:5]
	v_addc_co_u32_e32 v3, vcc, 0, v47, vcc
	v_lshlrev_b32_e32 v98, 16, v15
	v_and_b32_e32 v99, 0xffff0000, v15
	v_lshlrev_b32_e32 v100, 16, v16
	v_and_b32_e32 v102, 0xffff0000, v16
	v_lshlrev_b32_e32 v60, 16, v10
	v_and_b32_e32 v61, 0xffff0000, v10
	v_lshlrev_b32_e32 v62, 16, v11
	v_and_b32_e32 v106, 0xffff0000, v11
	v_lshlrev_b32_e32 v76, 16, v5
	v_lshlrev_b32_e32 v80, 16, v13
	v_and_b32_e32 v81, 0xffff0000, v13
	v_and_b32_e32 v77, 0xffff0000, v5
	v_and_b32_e32 v66, 0xffff0000, v22
	global_load_dwordx4 v[52:55], v[2:3], off offset:-4096
	global_load_dwordx4 v[4:7], v[0:1], off offset:48
	global_load_dwordx4 v[20:23], v[0:1], off offset:32
	global_load_dwordx4 v[122:125], v[0:1], off offset:16
	global_load_dwordx4 v[126:129], v[2:3], off
; __device__ __forceinline__ float bflo(unsigned w) { return __uint_as_float(w << 16); }
; __device__ __forceinline__ float bfhi(unsigned w) { return __uint_as_float(w & 0xFFFF0000u); }
; __device__ __forceinline__ float siluf(float v) { return v * __builtin_amdgcn_rcpf(1.f + __expf(-v)); }
; __device__ __forceinline__ float sigmf(float v) { return __builtin_amdgcn_rcpf(1.f + __expf(-v)); }
; __device__ void phase_post(const Params& p, int l) {
;     ...
;             float hv[32]; float s = 0.f;
; #pragma unroll
;             for (int q = 0; q < 4; ++q) { const u32x4 a = *(const u32x4*)(pr + c0 + q * 8), ab = *(const u32x4*)(p.HB + (size_t)row * 2048 + c0 + q * 8);
; #pragma unroll
;                 for (int e = 0; e < 4; ++e) { const float h0 = bflo(a[e]) + bflo(ab[e]), h1 = bfhi(a[e]) + bfhi(ab[e]); hv[q * 8 + 2 * e] = h0; hv[q * 8 + 2 * e + 1] = h1; s += h0 + h1; } }
;             s += __shfl_xor(s, 1, 64); s += __shfl_xor(s, 2, 64); s += __shfl_xor(s, 4, 64);
;             const float mean = s * (1.f / 256.f);
;             float q2 = 0.f;
; #pragma unroll
;             for (int e = 0; e < 32; ++e) { const float d = hv[e] - mean; q2 += d * d; }
;             q2 += __shfl_xor(q2, 1, 64); q2 += __shfl_xor(q2, 2, 64); q2 += __shfl_xor(q2, 4, 64);
;             const float rstd = rsqrtf(q2 * (1.f / 256.f) + LN_EPS);
;             const float* mw = p.mh_w + (size_t)l * 2048 + c0;
; #pragma unroll
;             for (int q = 0; q < 4; ++q) { const u32x4 ov = *(const u32x4*)(pr + 4096 + c0 + q * 8), zv = *(const u32x4*)(pr + 6144 + c0 + q * 8);
;                 const f32x4 wa = *(const f32x4*)(mw + q * 8), wb = *(const f32x4*)(mw + q * 8 + 4);
;                 float r[8];
; #pragma unroll
;                 for (int e = 0; e < 4; ++e) {
;                     const float m0 = (e < 2 ? wa[2 * e] : wb[2 * e - 4]), m1 = (e < 2 ? wa[2 * e + 1] : wb[2 * e - 3]);
;                     r[2 * e] = sigmf(bflo(ov[e])) * ((hv[q * 8 + 2 * e] - mean) * rstd * m0) * siluf(bflo(zv[e]));
;                     r[2 * e + 1] = sigmf(bfhi(ov[e])) * ((hv[q * 8 + 2 * e + 1] - mean) * rstd * m1) * siluf(bfhi(zv[e])); }
	s_nop 0
	global_load_dwordx4 v[0:3], v[8:9], off offset:48
	global_load_dwordx4 v[16:19], v[8:9], off offset:32
	global_load_dwordx4 v[130:133], v[8:9], off offset:16
	s_nop 0
	v_pk_add_f32 v[64:65], v[28:29], v[28:29] op_sel_hi:[0,1]
	v_lshlrev_b32_e32 v82, 16, v118
	v_mov_b64_e32 v[8:9], v[196:197]
	v_mov_b64_e32 v[10:11], v[198:199]
	v_mov_b64_e32 v[12:13], v[192:193]
	v_mov_b64_e32 v[14:15], v[194:195]
	v_and_b32_e32 v72, 0xffff0000, v118
	v_lshlrev_b32_e32 v118, 16, v25
	v_and_b32_e32 v64, 0xffff0000, v25
	v_and_b32_e32 v71, 0xffff0000, v87
	v_lshlrev_b32_e32 v74, 16, v91
	v_and_b32_e32 v75, 0xffff0000, v91
	v_pk_add_f32 v[108:109], v[70:71], v[74:75]
	v_lshlrev_b32_e32 v70, 16, v86
	v_and_b32_e32 v71, 0xffff0000, v86
	v_lshlrev_b32_e32 v74, 16, v90
	v_and_b32_e32 v75, 0xffff0000, v90
	v_pk_add_f32 v[110:111], v[70:71], v[74:75]
	v_mov_b32_e32 v70, v108
	v_mov_b32_e32 v71, v110
	v_mov_b32_e32 v74, v109
	v_mov_b32_e32 v75, v111
	v_pk_add_f32 v[86:87], v[70:71], v[74:75]
	v_lshlrev_b32_e32 v90, 16, v89
	v_and_b32_e32 v91, 0xffff0000, v89
	v_lshlrev_b32_e32 v134, 16, v121
	v_and_b32_e32 v68, 0xffff0000, v121
	v_pk_add_f32 v[76:77], v[76:77], v[80:81]
	v_pk_add_f32 v[56:57], v[56:57], v[60:61]
	v_mov_b32_e32 v79, v76
	v_mov_b32_e32 v83, v77
	v_pk_add_f32 v[78:79], v[78:79], v[82:83]
	v_mov_b32_e32 v59, v56
	v_mov_b32_e32 v63, v57
	v_pk_add_f32 v[58:59], v[58:59], v[62:63]
	s_waitcnt vmcnt(7)
	v_lshlrev_b32_e32 v25, 16, v52
	v_mul_f32_e32 v25, 0xbfb8aa3b, v25
	v_exp_f32_e32 v25, v25
	s_waitcnt vmcnt(3)
	v_lshlrev_b32_e32 v70, 16, v128
	v_and_b32_e32 v71, 0xffff0000, v128
	v_add_f32_e32 v25, 1.0, v25
	v_rcp_f32_e32 v46, v25
	v_and_b32_e32 v25, 0xffff0000, v52
	v_mul_f32_e32 v25, 0xbfb8aa3b, v25
	v_exp_f32_e32 v25, v25
	s_waitcnt vmcnt(1)
	v_lshlrev_b32_e32 v80, 16, v18
	v_and_b32_e32 v81, 0xffff0000, v18
	v_mul_f32_e32 v18, 0xbfb8aa3b, v80
	v_add_f32_e32 v25, 1.0, v25
	v_rcp_f32_e32 v47, v25
	v_lshlrev_b32_e32 v25, 16, v53
	v_mul_f32_e32 v25, 0xbfb8aa3b, v25
	v_exp_f32_e32 v25, v25
	v_exp_f32_e32 v18, v18
	v_lshlrev_b32_e32 v62, 16, v16
	v_and_b32_e32 v63, 0xffff0000, v16
	v_add_f32_e32 v25, 1.0, v25
	v_rcp_f32_e32 v50, v25
	v_and_b32_e32 v25, 0xffff0000, v53
	v_mul_f32_e32 v25, 0xbfb8aa3b, v25
	v_exp_f32_e32 v25, v25
	v_add_f32_e32 v18, 1.0, v18
	v_rcp_f32_e32 v82, v18
	v_mul_f32_e32 v18, 0xbfb8aa3b, v81
	v_add_f32_e32 v25, 1.0, v25
	v_rcp_f32_e32 v51, v25
	v_lshlrev_b32_e32 v25, 16, v54
	v_mul_f32_e32 v25, 0xbfb8aa3b, v25
	v_exp_f32_e32 v25, v25
	v_exp_f32_e32 v18, v18
	v_mul_f32_e32 v16, 0xbfb8aa3b, v62
	v_exp_f32_e32 v16, v16
	v_add_f32_e32 v25, 1.0, v25
	v_rcp_f32_e32 v52, v25
	v_and_b32_e32 v25, 0xffff0000, v54
	v_mul_f32_e32 v25, 0xbfb8aa3b, v25
	v_exp_f32_e32 v25, v25
	v_add_f32_e32 v18, 1.0, v18
	v_rcp_f32_e32 v83, v18
	v_add_f32_e32 v16, 1.0, v16
	v_add_f32_e32 v25, 1.0, v25
	v_rcp_f32_e32 v53, v25
	v_lshlrev_b32_e32 v25, 16, v55
	v_mul_f32_e32 v25, 0xbfb8aa3b, v25
	v_exp_f32_e32 v25, v25
	v_pk_mul_f32 v[80:81], v[82:83], v[80:81]
	v_lshlrev_b32_e32 v82, 16, v17
	v_and_b32_e32 v83, 0xffff0000, v17
	v_add_f32_e32 v25, 1.0, v25
	v_rcp_f32_e32 v54, v25
	v_and_b32_e32 v25, 0xffff0000, v55
	v_mul_f32_e32 v25, 0xbfb8aa3b, v25
	v_exp_f32_e32 v25, v25
	v_mul_f32_e32 v17, 0xbfb8aa3b, v82
	v_exp_f32_e32 v17, v17
	v_rcp_f32_e32 v16, v16
	v_add_f32_e32 v25, 1.0, v25
	v_rcp_f32_e32 v55, v25
	v_mul_f32_e32 v25, 0xbfb8aa3b, v70
	v_exp_f32_e32 v25, v25
	v_add_f32_e32 v17, 1.0, v17
	v_lshlrev_b32_e32 v146, 16, v19
	v_and_b32_e32 v147, 0xffff0000, v19
	v_add_f32_e32 v25, 1.0, v25
	v_rcp_f32_e32 v74, v25
	v_mul_f32_e32 v25, 0xbfb8aa3b, v71
	v_exp_f32_e32 v25, v25
	s_nop 0
	v_add_f32_e32 v25, 1.0, v25
	v_rcp_f32_e32 v75, v25
	s_nop 0
	v_pk_mul_f32 v[70:71], v[74:75], v[70:71]
	v_lshlrev_b32_e32 v74, 16, v85
	v_and_b32_e32 v75, 0xffff0000, v85
	v_pk_add_f32 v[136:137], v[74:75], v[90:91]
	v_lshlrev_b32_e32 v74, 16, v127
	v_mul_f32_e32 v25, 0xbfb8aa3b, v74
	v_exp_f32_e32 v25, v25
	v_and_b32_e32 v75, 0xffff0000, v127
	v_and_b32_e32 v85, 0xffff0000, v88
	v_add_f32_e32 v25, 1.0, v25
	v_rcp_f32_e32 v90, v25
	v_mul_f32_e32 v25, 0xbfb8aa3b, v75
	v_exp_f32_e32 v25, v25
	s_nop 0
	v_add_f32_e32 v25, 1.0, v25
	v_rcp_f32_e32 v91, v25
	s_nop 0
	v_pk_mul_f32 v[74:75], v[90:91], v[74:75]
	v_lshlrev_b32_e32 v90, 16, v84
	v_and_b32_e32 v91, 0xffff0000, v84
	v_lshlrev_b32_e32 v84, 16, v88
	v_pk_add_f32 v[138:139], v[90:91], v[84:85]
	v_mov_b32_e32 v84, v136
	v_mov_b32_e32 v85, v138
	v_mov_b32_e32 v88, v137
	v_mov_b32_e32 v89, v139
	v_pk_add_f32 v[88:89], v[84:85], v[88:89]
	v_lshlrev_b32_e32 v84, 16, v126
	v_mul_f32_e32 v33, 0xbfb8aa3b, v84
	v_exp_f32_e32 v33, v33
	v_and_b32_e32 v85, 0xffff0000, v126
	v_add_f32_e32 v25, 0, v89
	v_add_f32_e32 v25, v88, v25
	v_add_f32_e32 v33, 1.0, v33
	v_rcp_f32_e32 v90, v33
	v_mul_f32_e32 v33, 0xbfb8aa3b, v85
	v_exp_f32_e32 v33, v33
	v_add_f32_e32 v25, v87, v25
	v_add_f32_e32 v103, v86, v25
	v_and_b32_e32 v86, 0xffff0000, v24
	v_lshlrev_b32_e32 v87, 16, v24
	v_and_b32_e32 v24, 0xffff0000, v120
	v_lshlrev_b32_e32 v25, 16, v120
	v_add_f32_e32 v33, 1.0, v33
	v_pk_add_f32 v[120:121], v[86:87], v[24:25]
	v_lshlrev_b32_e32 v24, 16, v129
	v_rcp_f32_e32 v91, v33
	v_mul_f32_e32 v33, 0xbfb8aa3b, v24
	v_exp_f32_e32 v33, v33
	v_and_b32_e32 v25, 0xffff0000, v129
	v_pk_mul_f32 v[84:85], v[90:91], v[84:85]
	v_pk_add_f32 v[126:127], v[92:93], v[102:103]
	v_add_f32_e32 v33, 1.0, v33
	v_rcp_f32_e32 v86, v33
	v_mul_f32_e32 v33, 0xbfb8aa3b, v25
	v_exp_f32_e32 v33, v33
	s_waitcnt vmcnt(0)
; __device__ __forceinline__ float bflo(unsigned w) { return __uint_as_float(w << 16); }
; __device__ __forceinline__ float bfhi(unsigned w) { return __uint_as_float(w & 0xFFFF0000u); }
; __device__ __forceinline__ float siluf(float v) { return v * __builtin_amdgcn_rcpf(1.f + __expf(-v)); }
; __device__ __forceinline__ float sigmf(float v) { return __builtin_amdgcn_rcpf(1.f + __expf(-v)); }
; __device__ void phase_post(const Params& p, int l) {
;     ...
;             for (int q = 0; q < 4; ++q) { const u32x4 a = *(const u32x4*)(pr + c0 + q * 8), ab = *(const u32x4*)(p.HB + (size_t)row * 2048 + c0 + q * 8);
; #pragma unroll
;                 for (int e = 0; e < 4; ++e) { const float h0 = bflo(a[e]) + bflo(ab[e]), h1 = bfhi(a[e]) + bfhi(ab[e]); hv[q * 8 + 2 * e] = h0; hv[q * 8 + 2 * e + 1] = h1; s += h0 + h1; } }
;             s += __shfl_xor(s, 1, 64); s += __shfl_xor(s, 2, 64); s += __shfl_xor(s, 4, 64);
;             const float mean = s * (1.f / 256.f);
;             float q2 = 0.f;
; #pragma unroll
;             for (int e = 0; e < 32; ++e) { const float d = hv[e] - mean; q2 += d * d; }
;             q2 += __shfl_xor(q2, 1, 64); q2 += __shfl_xor(q2, 2, 64); q2 += __shfl_xor(q2, 4, 64);
;             const float rstd = rsqrtf(q2 * (1.f / 256.f) + LN_EPS);
;     ...
;                     r[2 * e] = sigmf(bflo(ov[e])) * ((hv[q * 8 + 2 * e] - mean) * rstd * m0) * siluf(bflo(zv[e]));
;                     r[2 * e + 1] = sigmf(bfhi(ov[e])) * ((hv[q * 8 + 2 * e + 1] - mean) * rstd * m1) * siluf(bfhi(zv[e])); }
	v_lshlrev_b32_e32 v102, 16, v132
	v_and_b32_e32 v103, 0xffff0000, v132
	v_mov_b32_e32 v119, v121
	v_add_f32_e32 v33, 1.0, v33
	v_rcp_f32_e32 v87, v33
	v_lshlrev_b32_e32 v33, 16, v123
	v_mul_f32_e32 v33, 0xbfb8aa3b, v33
	v_exp_f32_e32 v33, v33
	v_pk_mul_f32 v[86:87], v[86:87], v[24:25]
	v_lshlrev_b32_e32 v24, 16, v122
	v_and_b32_e32 v25, 0xffff0000, v122
	v_add_f32_e32 v33, 1.0, v33
	v_rcp_f32_e32 v88, v33
	v_and_b32_e32 v33, 0xffff0000, v123
	v_mul_f32_e32 v33, 0xbfb8aa3b, v33
	v_exp_f32_e32 v33, v33
	v_mov_b32_e32 v135, v120
	v_pk_add_f32 v[118:119], v[118:119], v[134:135]
	v_mul_f32_e32 v24, 0xbfb8aa3b, v24
	v_add_f32_e32 v33, 1.0, v33
	v_rcp_f32_e32 v89, v33
	v_lshlrev_b32_e32 v33, 16, v124
	v_mul_f32_e32 v33, 0xbfb8aa3b, v33
	v_exp_f32_e32 v33, v33
	v_mul_f32_e32 v25, 0xbfb8aa3b, v25
	v_exp_f32_e32 v24, v24
	v_exp_f32_e32 v25, v25
	v_add_f32_e32 v33, 1.0, v33
	v_rcp_f32_e32 v90, v33
	v_and_b32_e32 v33, 0xffff0000, v124
	v_mul_f32_e32 v33, 0xbfb8aa3b, v33
	v_exp_f32_e32 v33, v33
	v_add_f32_e32 v24, 1.0, v24
	v_add_f32_e32 v25, 1.0, v25
	v_rcp_f32_e32 v24, v24
	v_add_f32_e32 v33, 1.0, v33
	v_rcp_f32_e32 v91, v33
	v_lshlrev_b32_e32 v33, 16, v125
	v_mul_f32_e32 v33, 0xbfb8aa3b, v33
	v_exp_f32_e32 v33, v33
	v_rcp_f32_e32 v25, v25
	v_add_f32_e32 v33, 1.0, v33
	v_rcp_f32_e32 v92, v33
	v_and_b32_e32 v33, 0xffff0000, v125
	v_mul_f32_e32 v33, 0xbfb8aa3b, v33
	v_exp_f32_e32 v33, v33
	s_nop 0
	v_add_f32_e32 v33, 1.0, v33
	v_rcp_f32_e32 v93, v33
	v_mul_f32_e32 v33, 0xbfb8aa3b, v102
	v_exp_f32_e32 v33, v33
	s_nop 0
	v_add_f32_e32 v33, 1.0, v33
	v_rcp_f32_e32 v122, v33
	v_mul_f32_e32 v33, 0xbfb8aa3b, v103
	v_exp_f32_e32 v33, v33
	s_nop 0
	v_add_f32_e32 v33, 1.0, v33
	v_rcp_f32_e32 v123, v33
	s_nop 0
	v_pk_mul_f32 v[102:103], v[122:123], v[102:103]
	v_pk_add_f32 v[122:123], v[94:95], v[98:99]
	s_nop 0
	v_mov_b32_e32 v97, v122
	v_mov_b32_e32 v101, v123
	v_pk_add_f32 v[124:125], v[96:97], v[100:101]
	s_nop 0
	v_pk_add_f32 v[94:95], v[124:125], v[126:127]
	v_mov_b32_e32 v125, v126
	v_pk_add_f32 v[94:95], v[94:95], v[94:95] op_sel_hi:[0,1]
	v_lshlrev_b32_e32 v94, 16, v131
	v_mul_f32_e32 v33, 0xbfb8aa3b, v94
	v_exp_f32_e32 v33, v33
	v_mov_b32_e32 v107, v95
	v_and_b32_e32 v95, 0xffff0000, v131
	v_rcp_f32_e32 v126, v17
	v_add_f32_e32 v33, 1.0, v33
	v_rcp_f32_e32 v96, v33
	v_mul_f32_e32 v33, 0xbfb8aa3b, v95
	v_exp_f32_e32 v33, v33
	v_mul_f32_e32 v17, 0xbfb8aa3b, v83
	v_exp_f32_e32 v17, v17
	v_pk_add_f32 v[104:105], v[104:105], v[106:107]
	v_add_f32_e32 v33, 1.0, v33
	v_rcp_f32_e32 v97, v33
	v_add_f32_e32 v17, 1.0, v17
	v_rcp_f32_e32 v127, v17
	v_mul_f32_e32 v17, 0xbfb8aa3b, v63
	v_pk_mul_f32 v[94:95], v[96:97], v[94:95]
	v_lshlrev_b32_e32 v96, 16, v130
	v_mul_f32_e32 v33, 0xbfb8aa3b, v96
	v_exp_f32_e32 v33, v33
	v_and_b32_e32 v97, 0xffff0000, v130
	v_exp_f32_e32 v17, v17
	v_pk_add_f32 v[60:61], v[58:59], v[104:105]
	v_add_f32_e32 v33, 1.0, v33
	v_rcp_f32_e32 v98, v33
	v_mul_f32_e32 v33, 0xbfb8aa3b, v97
	v_exp_f32_e32 v33, v33
	v_add_f32_e32 v17, 1.0, v17
	v_rcp_f32_e32 v17, v17
	v_pk_add_f32 v[60:61], v[60:61], v[60:61] op_sel_hi:[0,1]
	v_add_f32_e32 v33, 1.0, v33
	v_rcp_f32_e32 v99, v33
	v_mov_b32_e32 v73, v61
	v_pk_add_f32 v[60:61], v[66:67], v[72:73]
	v_pk_mul_f32 v[16:17], v[16:17], v[62:63]
	v_pk_mul_f32 v[100:101], v[98:99], v[96:97]
	v_lshlrev_b32_e32 v96, 16, v133
	v_mul_f32_e32 v33, 0xbfb8aa3b, v96
	v_exp_f32_e32 v33, v33
	v_and_b32_e32 v97, 0xffff0000, v133
	v_pk_add_f32 v[62:63], v[78:79], v[60:61]
	v_mov_b32_e32 v59, v104
	v_add_f32_e32 v33, 1.0, v33
	v_rcp_f32_e32 v98, v33
	v_mul_f32_e32 v33, 0xbfb8aa3b, v97
	v_exp_f32_e32 v33, v33
	v_pk_add_f32 v[62:63], v[62:63], v[62:63] op_sel_hi:[0,1]
	v_mov_b32_e32 v69, v63
	v_pk_add_f32 v[62:63], v[64:65], v[68:69]
	v_add_f32_e32 v33, 1.0, v33
	v_rcp_f32_e32 v99, v33
	v_lshlrev_b32_e32 v33, 16, v20
	v_mul_f32_e32 v33, 0xbfb8aa3b, v33
	v_exp_f32_e32 v33, v33
	v_pk_mul_f32 v[98:99], v[98:99], v[96:97]
	v_pk_add_f32 v[64:65], v[118:119], v[62:63]
	v_mov_b32_e32 v63, v118
	v_add_f32_e32 v33, 1.0, v33
	v_rcp_f32_e32 v96, v33
	v_lshlrev_b32_e32 v33, 16, v22
	v_mul_f32_e32 v33, 0xbfb8aa3b, v33
	v_exp_f32_e32 v33, v33
	v_add_f32_e32 v18, v64, v65
	v_mov_b32_e32 v79, v60
	v_pk_mul_f32 v[82:83], v[126:127], v[82:83]
	v_add_f32_e32 v33, 1.0, v33
	v_rcp_f32_e32 v106, v33
	ds_bpermute_b32 v33, v117, v18
	v_and_b32_e32 v20, 0xffff0000, v20
	v_and_b32_e32 v22, 0xffff0000, v22
	v_mul_f32_e32 v20, 0xbfb8aa3b, v20
	v_mul_f32_e32 v22, 0xbfb8aa3b, v22
	s_waitcnt lgkmcnt(0)
	v_add_f32_e32 v18, v18, v33
	ds_bpermute_b32 v33, v116, v18
	v_exp_f32_e32 v20, v20
	v_exp_f32_e32 v22, v22
	s_waitcnt lgkmcnt(0)
	v_add_f32_e32 v18, v18, v33
	ds_bpermute_b32 v33, v115, v18
	v_add_f32_e32 v20, 1.0, v20
	v_add_f32_e32 v22, 1.0, v22
	v_rcp_f32_e32 v97, v20
	v_lshlrev_b32_e32 v20, 16, v21
	s_waitcnt lgkmcnt(0)
; __device__ void phase_post(const Params& p, int l) {
;     ...
;             const float mean = s * (1.f / 256.f);
;             float q2 = 0.f;
; #pragma unroll
;             for (int e = 0; e < 32; ++e) { const float d = hv[e] - mean; q2 += d * d; }
;             q2 += __shfl_xor(q2, 1, 64); q2 += __shfl_xor(q2, 2, 64); q2 += __shfl_xor(q2, 4, 64);
;             const float rstd = rsqrtf(q2 * (1.f / 256.f) + LN_EPS);
	v_add_f32_e32 v18, v18, v33
	v_mul_f32_e32 v18, 0x3b800000, v18
	v_pk_add_f32 v[64:65], v[138:139], v[18:19] op_sel_hi:[1,0] neg_lo:[0,1] neg_hi:[0,1]
	v_pk_add_f32 v[68:69], v[136:137], v[18:19] op_sel_hi:[1,0] neg_lo:[0,1] neg_hi:[0,1]
	v_pk_add_f32 v[110:111], v[110:111], v[18:19] op_sel_hi:[1,0] neg_lo:[0,1] neg_hi:[0,1]
	v_pk_add_f32 v[108:109], v[108:109], v[18:19] op_sel_hi:[1,0] neg_lo:[0,1] neg_hi:[0,1]
	v_pk_add_f32 v[122:123], v[122:123], v[18:19] op_sel_hi:[1,0] neg_lo:[0,1] neg_hi:[0,1]
	v_pk_add_f32 v[56:57], v[56:57], v[18:19] op_sel_hi:[1,0] neg_lo:[0,1] neg_hi:[0,1]
	v_pk_add_f32 v[76:77], v[76:77], v[18:19] op_sel_hi:[1,0] neg_lo:[0,1] neg_hi:[0,1]
	v_pk_add_f32 v[120:121], v[120:121], v[18:19] op_sel_hi:[1,0] neg_lo:[0,1] neg_hi:[0,1]
	v_pk_add_f32 v[62:63], v[62:63], v[18:19] op_sel_hi:[1,0] neg_lo:[0,1] neg_hi:[0,1]
	v_pk_add_f32 v[30:31], v[30:31], v[18:19] op_sel_hi:[1,0] neg_lo:[0,1] neg_hi:[0,1]
	v_pk_add_f32 v[124:125], v[124:125], v[18:19] op_sel_hi:[1,0] neg_lo:[0,1] neg_hi:[0,1]
	v_pk_add_f32 v[26:27], v[26:27], v[18:19] op_sel_hi:[1,0] neg_lo:[0,1] neg_hi:[0,1]
	v_pk_add_f32 v[48:49], v[48:49], v[18:19] op_sel_hi:[1,0] neg_lo:[0,1] neg_hi:[0,1]
	v_pk_add_f32 v[58:59], v[58:59], v[18:19] op_sel_hi:[1,0] neg_lo:[0,1] neg_hi:[0,1]
	v_mul_f32_e32 v19, 0xbfb8aa3b, v146
	v_exp_f32_e32 v19, v19
	v_pk_mul_f32 v[66:67], v[64:65], v[64:65]
	v_pk_mul_f32 v[72:73], v[68:69], v[68:69]
	v_pk_mul_f32 v[126:127], v[110:111], v[110:111]
	v_add_f32_e32 v19, 1.0, v19
	v_rcp_f32_e32 v150, v19
	v_mul_f32_e32 v19, 0xbfb8aa3b, v147
	v_exp_f32_e32 v19, v19
	v_pk_mul_f32 v[128:129], v[108:109], v[108:109]
	v_pk_mul_f32 v[142:143], v[26:27], v[26:27]
	v_pk_mul_f32 v[130:131], v[122:123], v[122:123]
	v_add_f32_e32 v19, 1.0, v19
	v_rcp_f32_e32 v151, v19
	v_lshlrev_b32_e32 v19, 16, v4
	v_mul_f32_e32 v19, 0xbfb8aa3b, v19
	v_exp_f32_e32 v19, v19
	v_pk_mul_f32 v[146:147], v[150:151], v[146:147]
	v_pk_mul_f32 v[140:141], v[124:125], v[124:125]
	v_pk_mul_f32 v[138:139], v[30:31], v[30:31]
	v_add_f32_e32 v19, 1.0, v19
	v_rcp_f32_e32 v150, v19
	v_pk_add_f32 v[28:29], v[28:29], v[18:19] op_sel_hi:[1,0] neg_lo:[0,1] neg_hi:[0,1]
	v_pk_add_f32 v[18:19], v[78:79], v[18:19] op_sel_hi:[1,0] neg_lo:[0,1] neg_hi:[0,1]
	v_lshlrev_b32_e32 v78, 16, v0
	v_and_b32_e32 v79, 0xffff0000, v0
	v_mul_f32_e32 v0, 0xbfb8aa3b, v78
	v_exp_f32_e32 v0, v0
	v_pk_mul_f32 v[132:133], v[56:57], v[56:57]
	v_pk_mul_f32 v[104:105], v[58:59], v[58:59]
	v_pk_mul_f32 v[144:145], v[48:49], v[48:49]
	v_add_f32_e32 v0, 1.0, v0
	v_rcp_f32_e32 v158, v0
	v_mul_f32_e32 v0, 0xbfb8aa3b, v79
	v_exp_f32_e32 v0, v0
	v_pk_mul_f32 v[134:135], v[76:77], v[76:77]
	v_pk_mul_f32 v[60:61], v[18:19], v[18:19]
	v_pk_mul_f32 v[152:153], v[28:29], v[28:29]
	v_add_f32_e32 v0, 1.0, v0
	v_rcp_f32_e32 v159, v0
	v_add_f32_e32 v0, v66, v67
	v_add_f32_e32 v0, v72, v0
	v_add_f32_e32 v0, v73, v0
	v_add_f32_e32 v0, v126, v0
	v_add_f32_e32 v0, v127, v0
	v_add_f32_e32 v0, v128, v0
	v_add_f32_e32 v0, v129, v0
	v_add_f32_e32 v0, v142, v0
	v_add_f32_e32 v0, v143, v0
	v_add_f32_e32 v0, v130, v0
	v_add_f32_e32 v0, v131, v0
	v_add_f32_e32 v0, v140, v0
	v_add_f32_e32 v0, v141, v0
	v_add_f32_e32 v0, v138, v0
	v_add_f32_e32 v0, v139, v0
	v_add_f32_e32 v0, v132, v0
	v_add_f32_e32 v0, v133, v0
	v_add_f32_e32 v0, v104, v0
	v_add_f32_e32 v0, v105, v0
	v_add_f32_e32 v0, v144, v0
	v_add_f32_e32 v0, v145, v0
	v_add_f32_e32 v0, v134, v0
	v_add_f32_e32 v0, v135, v0
	v_add_f32_e32 v0, v60, v0
	v_add_f32_e32 v0, v61, v0
	v_add_f32_e32 v0, v152, v0
	v_pk_mul_f32 v[136:137], v[120:121], v[120:121]
	v_add_f32_e32 v0, v153, v0
	v_add_f32_e32 v0, v137, v0
	v_pk_mul_f32 v[118:119], v[62:63], v[62:63]
	v_add_f32_e32 v0, v136, v0
	v_add_f32_e32 v0, v119, v0
	v_add_f32_e32 v0, v118, v0
	ds_bpermute_b32 v33, v117, v0
	v_and_b32_e32 v21, 0xffff0000, v21
	v_rcp_f32_e32 v107, v22
	v_lshlrev_b32_e32 v22, 16, v23
	v_and_b32_e32 v23, 0xffff0000, v23
	s_waitcnt lgkmcnt(0)
	v_add_f32_e32 v0, v0, v33
	ds_bpermute_b32 v33, v116, v0
	v_mul_f32_e32 v20, 0xbfb8aa3b, v20
	v_mul_f32_e32 v21, 0xbfb8aa3b, v21
	v_mul_f32_e32 v22, 0xbfb8aa3b, v22
	v_mul_f32_e32 v23, 0xbfb8aa3b, v23
	s_waitcnt lgkmcnt(0)
	v_add_f32_e32 v0, v0, v33
	ds_bpermute_b32 v33, v115, v0
	v_exp_f32_e32 v20, v20
	v_exp_f32_e32 v21, v21
	v_exp_f32_e32 v22, v22
	v_exp_f32_e32 v23, v23
	s_waitcnt lgkmcnt(0)
	v_add_f32_e32 v0, v0, v33
	v_fmamk_f32 v0, v0, 0x3b800000, v207
	v_cmp_gt_f32_e32 vcc, s41, v0
	v_mul_f32_e32 v33, 0x4b800000, v0
	v_add_f32_e32 v20, 1.0, v20
	v_cndmask_b32_e32 v0, v0, v33, vcc
	v_rsq_f32_e32 v0, v0
	v_add_f32_e32 v21, 1.0, v21
	v_add_f32_e32 v22, 1.0, v22
	v_add_f32_e32 v23, 1.0, v23
	v_mul_f32_e32 v33, 0x45800000, v0
	v_cndmask_b32_e32 v0, v0, v33, vcc
	v_pk_mul_f32 v[60:61], v[64:65], v[0:1] op_sel_hi:[1,0]
	v_pk_mul_f32 v[26:27], v[26:27], v[0:1] op_sel_hi:[1,0]
	s_waitcnt vmcnt(0)
; __device__ __forceinline__ float bflo(unsigned w) { return __uint_as_float(w << 16); }
; __device__ __forceinline__ float bfhi(unsigned w) { return __uint_as_float(w & 0xFFFF0000u); }
; __device__ __forceinline__ unsigned pk2(float lo, float hi) { const f32x2_t v = {lo, hi}; return __builtin_bit_cast(unsigned, __builtin_convertvector(v, bf16x2_t)); }
; __device__ __forceinline__ float siluf(float v) { return v * __builtin_amdgcn_rcpf(1.f + __expf(-v)); }
; __device__ __forceinline__ float sigmf(float v) { return __builtin_amdgcn_rcpf(1.f + __expf(-v)); }
; __device__ void phase_post(const Params& p, int l) {
;     ...
;             const float* mw = p.mh_w + (size_t)l * 2048 + c0;
; #pragma unroll
;             for (int q = 0; q < 4; ++q) { const u32x4 ov = *(const u32x4*)(pr + 4096 + c0 + q * 8), zv = *(const u32x4*)(pr + 6144 + c0 + q * 8);
;                 const f32x4 wa = *(const f32x4*)(mw + q * 8), wb = *(const f32x4*)(mw + q * 8 + 4);
;                 float r[8];
; #pragma unroll
;                 for (int e = 0; e < 4; ++e) {
;                     const float m0 = (e < 2 ? wa[2 * e] : wb[2 * e - 4]), m1 = (e < 2 ? wa[2 * e + 1] : wb[2 * e - 3]);
;                     r[2 * e] = sigmf(bflo(ov[e])) * ((hv[q * 8 + 2 * e] - mean) * rstd * m0) * siluf(bflo(zv[e]));
;                     r[2 * e + 1] = sigmf(bfhi(ov[e])) * ((hv[q * 8 + 2 * e + 1] - mean) * rstd * m1) * siluf(bfhi(zv[e])); }
;                 u32x4 o; o.x = pk2(r[0], r[1]); o.y = pk2(r[2], r[3]); o.z = pk2(r[4], r[5]); o.w = pk2(r[6], r[7]);
;                 *(u32x4*)(pr + 9216 + c0 + q * 8) = o; }
;         }
	v_pk_mul_f32 v[12:13], v[12:13], v[60:61]
	v_rcp_f32_e32 v20, v20
	v_pk_mul_f32 v[12:13], v[46:47], v[12:13]
	v_pk_mul_f32 v[46:47], v[68:69], v[0:1] op_sel_hi:[1,0]
	v_pk_mul_f32 v[12:13], v[84:85], v[12:13]
	v_pk_mul_f32 v[14:15], v[14:15], v[46:47]
	v_pk_mul_f32 v[46:47], v[110:111], v[0:1] op_sel_hi:[1,0]
	v_pk_mul_f32 v[14:15], v[50:51], v[14:15]
	v_pk_mul_f32 v[8:9], v[8:9], v[46:47]
	v_pk_mul_f32 v[14:15], v[74:75], v[14:15]
	v_pk_mul_f32 v[8:9], v[52:53], v[8:9]
	v_rcp_f32_e32 v21, v21
	v_pk_mul_f32 v[46:47], v[70:71], v[8:9]
	v_pk_mul_f32 v[8:9], v[108:109], v[0:1] op_sel_hi:[1,0]
	v_rcp_f32_e32 v22, v22
	v_pk_mul_f32 v[8:9], v[10:11], v[8:9]
	v_cvt_pk_bf16_f32 v10, v46, v47
	v_pk_mul_f32 v[8:9], v[54:55], v[8:9]
	v_rcp_f32_e32 v23, v23
	v_pk_mul_f32 v[50:51], v[86:87], v[8:9]
	v_cvt_pk_bf16_f32 v8, v12, v13
	v_cvt_pk_bf16_f32 v9, v14, v15
	v_cvt_pk_bf16_f32 v11, v50, v51
	global_store_dwordx4 v[44:45], v[8:11], off offset:2048
	v_mov_b64_e32 v[12:13], v[200:201]
	v_mov_b64_e32 v[14:15], v[202:203]
	v_mov_b64_e32 v[8:9], v[224:225]
	v_mov_b64_e32 v[10:11], v[226:227]
	v_and_b32_e32 v4, 0xffff0000, v4
	v_mul_f32_e32 v4, 0xbfb8aa3b, v4
	v_exp_f32_e32 v4, v4
	v_pk_mul_f32 v[78:79], v[158:159], v[78:79]
	v_cmp_lt_i32_e32 vcc, s68, v32
	s_or_b64 s[14:15], vcc, s[14:15]
	v_add_f32_e32 v4, 1.0, v4
	v_rcp_f32_e32 v151, v4
	v_lshlrev_b32_e32 v4, 16, v5
	v_and_b32_e32 v5, 0xffff0000, v5
	v_mul_f32_e32 v4, 0xbfb8aa3b, v4
	v_mul_f32_e32 v5, 0xbfb8aa3b, v5
	v_exp_f32_e32 v4, v4
	v_exp_f32_e32 v5, v5
	v_add_f32_e32 v4, 1.0, v4
	v_add_f32_e32 v5, 1.0, v5
	v_rcp_f32_e32 v4, v4
	v_rcp_f32_e32 v5, v5
	v_pk_mul_f32 v[12:13], v[12:13], v[26:27]
	s_nop 0
	v_pk_mul_f32 v[12:13], v[24:25], v[12:13]
	v_pk_mul_f32 v[24:25], v[122:123], v[0:1] op_sel_hi:[1,0]
	v_pk_mul_f32 v[12:13], v[100:101], v[12:13]
	v_pk_mul_f32 v[14:15], v[14:15], v[24:25]
	v_pk_mul_f32 v[24:25], v[124:125], v[0:1] op_sel_hi:[1,0]
	v_pk_mul_f32 v[14:15], v[88:89], v[14:15]
	v_pk_mul_f32 v[8:9], v[8:9], v[24:25]
	v_pk_mul_f32 v[14:15], v[94:95], v[14:15]
	v_pk_mul_f32 v[8:9], v[90:91], v[8:9]
	s_nop 0
	v_pk_mul_f32 v[24:25], v[102:103], v[8:9]
	v_pk_mul_f32 v[8:9], v[30:31], v[0:1] op_sel_hi:[1,0]
	s_nop 0
	v_pk_mul_f32 v[8:9], v[10:11], v[8:9]
	v_cvt_pk_bf16_f32 v10, v24, v25
	v_pk_mul_f32 v[8:9], v[92:93], v[8:9]
	v_pk_mul_f32 v[24:25], v[56:57], v[0:1] op_sel_hi:[1,0]
	v_pk_mul_f32 v[26:27], v[98:99], v[8:9]
	v_cvt_pk_bf16_f32 v8, v12, v13
	v_cvt_pk_bf16_f32 v9, v14, v15
	v_cvt_pk_bf16_f32 v11, v26, v27
	global_store_dwordx4 v[44:45], v[8:11], off offset:2064
	v_mov_b64_e32 v[12:13], v[228:229]
	v_mov_b64_e32 v[14:15], v[230:231]
	v_mov_b64_e32 v[8:9], v[232:233]
	v_mov_b64_e32 v[10:11], v[234:235]
	v_pk_mul_f32 v[12:13], v[12:13], v[24:25]
	s_nop 0
	v_pk_mul_f32 v[12:13], v[96:97], v[12:13]
	s_nop 0
	v_pk_mul_f32 v[12:13], v[16:17], v[12:13]
	v_pk_mul_f32 v[16:17], v[58:59], v[0:1] op_sel_hi:[1,0]
	s_nop 0
	v_pk_mul_f32 v[14:15], v[14:15], v[16:17]
	v_pk_mul_f32 v[16:17], v[48:49], v[0:1] op_sel_hi:[1,0]
	v_pk_mul_f32 v[14:15], v[20:21], v[14:15]
	v_pk_mul_f32 v[8:9], v[8:9], v[16:17]
	v_pk_mul_f32 v[14:15], v[82:83], v[14:15]
	v_pk_mul_f32 v[8:9], v[106:107], v[8:9]
	s_nop 0
	v_pk_mul_f32 v[16:17], v[80:81], v[8:9]
	v_pk_mul_f32 v[8:9], v[76:77], v[0:1] op_sel_hi:[1,0]
	s_nop 0
	v_pk_mul_f32 v[8:9], v[10:11], v[8:9]
	v_cvt_pk_bf16_f32 v10, v16, v17
	v_pk_mul_f32 v[8:9], v[22:23], v[8:9]
	v_pk_mul_f32 v[16:17], v[18:19], v[0:1] op_sel_hi:[1,0]
	v_pk_mul_f32 v[20:21], v[146:147], v[8:9]
	v_cvt_pk_bf16_f32 v8, v12, v13
	v_cvt_pk_bf16_f32 v9, v14, v15
	v_cvt_pk_bf16_f32 v11, v20, v21
	global_store_dwordx4 v[44:45], v[8:11], off offset:2080
	v_mov_b64_e32 v[12:13], v[236:237]
	v_mov_b64_e32 v[14:15], v[238:239]
	v_mov_b64_e32 v[8:9], v[240:241]
	v_mov_b64_e32 v[10:11], v[242:243]
	v_pk_mul_f32 v[12:13], v[12:13], v[16:17]
	v_lshlrev_b32_e32 v16, 16, v1
	v_and_b32_e32 v17, 0xffff0000, v1
	v_mul_f32_e32 v1, 0xbfb8aa3b, v16
	v_exp_f32_e32 v1, v1
	v_pk_mul_f32 v[12:13], v[150:151], v[12:13]
	v_add_f32_e32 v1, 1.0, v1
	v_rcp_f32_e32 v18, v1
	v_pk_mul_f32 v[20:21], v[28:29], v[0:1] op_sel_hi:[1,0]
	v_mul_f32_e32 v1, 0xbfb8aa3b, v17
	v_exp_f32_e32 v1, v1
	v_pk_mul_f32 v[14:15], v[14:15], v[20:21]
	v_pk_mul_f32 v[12:13], v[78:79], v[12:13]
	v_pk_mul_f32 v[4:5], v[4:5], v[14:15]
	v_add_f32_e32 v1, 1.0, v1
	v_rcp_f32_e32 v19, v1
	v_lshlrev_b32_e32 v1, 16, v6
	v_mul_f32_e32 v1, 0xbfb8aa3b, v1
	v_exp_f32_e32 v1, v1
	v_pk_mul_f32 v[14:15], v[18:19], v[16:17]
	v_lshlrev_b32_e32 v16, 16, v2
	v_pk_mul_f32 v[4:5], v[14:15], v[4:5]
	v_add_f32_e32 v1, 1.0, v1
	v_rcp_f32_e32 v14, v1
	v_and_b32_e32 v1, 0xffff0000, v6
	v_mul_f32_e32 v1, 0xbfb8aa3b, v1
	v_exp_f32_e32 v1, v1
	v_and_b32_e32 v17, 0xffff0000, v2
	v_lshlrev_b32_e32 v2, 16, v3
	v_and_b32_e32 v3, 0xffff0000, v3
	v_add_f32_e32 v1, 1.0, v1
	v_rcp_f32_e32 v15, v1
	v_mul_f32_e32 v1, 0xbfb8aa3b, v16
	v_exp_f32_e32 v1, v1
	s_nop 0
	v_add_f32_e32 v1, 1.0, v1
	v_rcp_f32_e32 v18, v1
	v_pk_mul_f32 v[20:21], v[120:121], v[0:1] op_sel_hi:[1,0]
	v_mul_f32_e32 v1, 0xbfb8aa3b, v17
	v_exp_f32_e32 v1, v1
	v_pk_mul_f32 v[8:9], v[8:9], v[20:21] op_sel:[0,1] op_sel_hi:[1,0]
	v_add_f32_e32 v1, 1.0, v1
	v_rcp_f32_e32 v19, v1
	v_lshlrev_b32_e32 v1, 16, v7
	v_mul_f32_e32 v1, 0xbfb8aa3b, v1
	v_exp_f32_e32 v1, v1
	v_pk_mul_f32 v[8:9], v[14:15], v[8:9]
	v_pk_mul_f32 v[14:15], v[18:19], v[16:17]
	v_add_f32_e32 v1, 1.0, v1
	v_rcp_f32_e32 v6, v1
	v_and_b32_e32 v1, 0xffff0000, v7
	v_mul_f32_e32 v1, 0xbfb8aa3b, v1
	v_exp_f32_e32 v1, v1
	v_pk_mul_f32 v[8:9], v[14:15], v[8:9]
	v_add_f32_e32 v1, 1.0, v1
	v_rcp_f32_e32 v7, v1
	v_mul_f32_e32 v1, 0xbfb8aa3b, v2
	v_exp_f32_e32 v1, v1
	s_nop 0
	v_add_f32_e32 v1, 1.0, v1
	v_rcp_f32_e32 v14, v1
	v_pk_mul_f32 v[0:1], v[62:63], v[0:1] op_sel_hi:[1,0]
	s_nop 0
	v_pk_mul_f32 v[0:1], v[10:11], v[0:1] op_sel:[0,1] op_sel_hi:[1,0]
	s_nop 0
	v_pk_mul_f32 v[0:1], v[6:7], v[0:1]
	v_mul_f32_e32 v6, 0xbfb8aa3b, v3
	v_exp_f32_e32 v6, v6
	s_nop 0
	v_add_f32_e32 v6, 1.0, v6
	v_rcp_f32_e32 v15, v6
	s_nop 0
	v_pk_mul_f32 v[2:3], v[14:15], v[2:3]
	s_nop 0
	v_pk_mul_f32 v[6:7], v[2:3], v[0:1]
	v_cvt_pk_bf16_f32 v0, v12, v13
	v_cvt_pk_bf16_f32 v1, v4, v5
	v_cvt_pk_bf16_f32 v2, v8, v9
	v_cvt_pk_bf16_f32 v3, v6, v7
	global_store_dwordx4 v[44:45], v[0:3], off offset:2096
	s_andn2_b64 exec, exec, s[14:15]
	s_cbranch_execnz .LBB0_12

; #define TIDX tid_()
; template <bool ISM>
; __device__ void scan_item(const Params& p, int l, int item, unsigned char* lds) {
;     constexpr int NT = ISM ? 5 : 4;
;     constexpr float L2E = 1.4426950408889634f;
;     const int tid = TIDX, wid = __builtin_amdgcn_readfirstlane(tid >> 6), lane = tid & 63, fr = lane & 15, fq = lane >> 4;
;     const int trq = fr >> 2, trp = fr & 3;
;     const int sl = ISM ? (item & 3) : 0, dir = ISM ? ((item >> 2) & 1) : (item & 1), h = ISM ? ((item >> 3) & 7) : ((item >> 1) & 31), b = item >> 6;
;     const int qcol = ISM ? h * 128 : 2048 + 2560 + (h >> 3) * 128;
;     const int kcol = ISM ? 1024 + h * 128 : 2048 + 2048 + (h >> 3) * 128;
;     const int vcol = ISM ? 2048 + h * 256 + sl * 64 : 2048 + h * 64;
;     const int ocol = ISM ? h * 256 + sl * 64 : h * 64;
;     u16* const obase = dir ? (ISM ? p.HB : p.YB) : (ISM ? p.P : p.P + 8192);
;     const unsigned ostride = dir ? 2048u : (unsigned)PW;
;     u16* Ks = (u16*)(lds + LS_K); u16* Vs = (u16*)(lds + LS_V); u16* Vw = (u16*)(lds + LS_VW); u16* CT = (u16*)(lds + LS_CT);
;     float* F = (float*)(lds + LS_F);
;     float *f_c = F, *f_r = F + 128, *f_wi = F + 256, *f_ws = F + 384, *f_em = F + 512;
;     const unsigned ldsb = (unsigned)(size_t)(LAS unsigned char*)lds;
;     const unsigned trK = ldsb + LS_K + (unsigned)(((fq * 8 + trq) * LDK + 16 * wid + 4 * trp) * 2);
;     const unsigned trVw = ldsb + LS_VW + (unsigned)(((fq * 8 + trq) * LDV + 4 * trp) * 2);
;     const unsigned trV = ldsb + LS_V + (unsigned)(((fq * 4 + trq) * LDV + 4 * trp) * 2);
;     const float Dh = ISM ? 0.f : p.d_skip[l * 32 + h];
;     const u16* __restrict__ gQKX = p.QKX; const u16* __restrict__ gP = p.P; const float* __restrict__ gG2 = p.G2;
;     const int gcol = ISM ? (dir * 8 + h) * 3 : 48 + (dir * 32 + h) * 2;
;     __syncthreads();
;     for (int i = tid; i < 128 * 24; i += 512) { const int r = i / 24, cc = 64 + i % 24; Vs[r * LDV + cc] = (ISM && cc == 64) ? (u16)0x3F80 : (u16)0; Vw[r * LDV + cc] = 0; }
;     for (int i = tid; i < 80 * LDK; i += 512) CT[i] = 0;
;     f32x4 st[NT];
; #pragma unroll
;     for (int m = 0; m < NT; ++m) st[m] = (f32x4){0.f, 0.f, 0.f, 0.f};
;     float m_prev = 0.f;
;     unsigned qo, ko[4], vo[2], go, ge, oo[4];
;     bf16x8 qf[4]; u32x4 kr[4]; u32x4 vr[2]; f32x3 gv = {0.f, 0.f, 0.f}; float e0 = 0.f, e1 = 0.f;
;     ...
;     SCAN_PTRS(0); SCAN_LOAD();
.LBB0_27:
	s_or_b64 exec, exec, s[4:5]
	s_lshl_b32 s4, s8, 4
	s_and_b32 s4, s4, 0x180
	v_or_b32_e32 v1, s4, v25
	s_and_b32 s15, s68, 0xffffffc0
	v_or_b32_e32 v20, 0x1200, v1
	v_lshlrev_b32_e32 v1, 3, v24
	s_and_b32 s13, s68, 1
	s_addk_i32 s15, 0xff80
	s_ashr_i32 s18, s10, 6
	s_cmp_lt_i32 s18, 4
	s_cbranch_scc1 .Lwid_keep_s
	s_sub_i32 s18, 11, s18
.Lwid_keep_s:
	s_lshl_b32 s14, s3, 6
	v_and_b32_e32 v34, 0x78, v1
	s_cmp_eq_u32 s13, 0
	v_or_b32_e32 v2, s4, v34
	v_ashrrev_i32_e32 v29, 4, v24
	s_cselect_b64 s[6:7], -1, 0
	v_or_b32_e32 v16, 0x1000, v2
	v_sub_u32_e32 v2, 0xff, v29
	s_lshl_b32 s12, s15, 2
	v_cndmask_b32_e64 v2, v2, v29, s[6:7]
	v_add_u32_e32 v2, s12, v2
	v_mad_u64_u32 v[150:151], s[4:5], v2, s92, v[16:17]
	v_add_u32_e32 v2, 0x200, v24
	v_ashrrev_i32_e32 v28, 4, v2
	v_sub_u32_e32 v3, 0xff, v28
	v_cndmask_b32_e64 v3, v3, v28, s[6:7]
	v_add_u32_e32 v3, s12, v3
	v_mad_u64_u32 v[152:153], s[4:5], v3, s92, v[16:17]
	v_add_u32_e32 v3, 0x400, v24
	v_ashrrev_i32_e32 v27, 4, v3
	v_sub_u32_e32 v3, 0xff, v27
	v_and_b32_e32 v35, 56, v1
	s_lshl_b32 s11, s18, 4
	v_cndmask_b32_e64 v3, v3, v27, s[6:7]
	v_or_b32_e32 v1, s14, v35
	v_ashrrev_i32_e32 v22, 3, v24
	v_or_b32_e32 v30, s11, v19
	v_add_u32_e32 v3, s12, v3
	v_or_b32_e32 v18, 0x800, v1
	v_sub_u32_e32 v1, 0xff, v22
	v_sub_u32_e32 v0, 0xff, v30
	v_mad_u64_u32 v[158:159], s[4:5], v3, s92, v[16:17]
	v_add_u32_e32 v3, 0x600, v24
	v_cndmask_b32_e64 v1, v1, v22, s[6:7]
	v_cndmask_b32_e64 v0, v0, v30, s[6:7]
	v_ashrrev_i32_e32 v26, 4, v3
	v_add_u32_e32 v1, s12, v1
	v_ashrrev_i32_e32 v23, 3, v2
	v_add_u32_e32 v0, s12, v0
	v_sub_u32_e32 v3, 0xff, v26
	v_mad_u64_u32 v[164:165], s[4:5], v1, s92, v[18:19]
	v_sub_u32_e32 v1, 0xff, v23
	v_cndmask_b32_e64 v3, v3, v26, s[6:7]
	v_cndmask_b32_e64 v1, v1, v23, s[6:7]
	v_mad_u64_u32 v[162:163], s[4:5], v0, s92, v[20:21]
	v_add_u32_e32 v3, s12, v3
	v_add_u32_e32 v1, s12, v1
	v_mov_b32_e32 v163, v149
	v_mad_u64_u32 v[160:161], s[4:5], v3, s92, v[16:17]
	v_mad_u64_u32 v[166:167], s[4:5], v1, s92, v[18:19]
	v_lshl_add_u64 v[0:1], v[162:163], 1, s[72:73]
	global_load_dwordx4 v[68:71], v[0:1], off
	global_load_dwordx4 v[64:67], v[0:1], off offset:64
	global_load_dwordx4 v[60:63], v[0:1], off offset:128
	global_load_dwordx4 v[56:59], v[0:1], off offset:192
	v_mov_b32_e32 v151, v149
	v_mov_b32_e32 v153, v149
	v_mov_b32_e32 v159, v149
	v_mov_b32_e32 v161, v149
	v_mov_b32_e32 v165, v149
	v_lshl_add_u64 v[0:1], v[150:151], 1, s[72:73]
	v_lshl_add_u64 v[4:5], v[152:153], 1, s[72:73]
	v_lshl_add_u64 v[8:9], v[158:159], 1, s[72:73]
	v_lshl_add_u64 v[12:13], v[160:161], 1, s[72:73]
	v_lshl_add_u64 v[36:37], v[164:165], 1, s[72:73]
	v_mov_b32_e32 v167, v149
	global_load_dwordx4 v[0:3], v[0:1], off
	s_nop 0
	global_load_dwordx4 v[4:7], v[4:5], off
	s_nop 0
	global_load_dwordx4 v[8:11], v[8:9], off
	s_nop 0
	global_load_dwordx4 v[12:15], v[12:13], off
	v_lshl_add_u64 v[38:39], v[166:167], 1, s[72:73]
	global_load_dwordx4 v[76:79], v[36:37], off
	global_load_dwordx4 v[72:75], v[38:39], off
	v_and_b32_e32 v36, 0x7f, v24
	v_bitop3_b32 v37, v24, s2, v217 bitop3:0x6c
	s_lshl_b32 s4, s13, 6
	s_lshl_b32 s3, s3, 1
	v_cndmask_b32_e64 v37, v37, v36, s[6:7]
	s_or_b32 s16, s3, s4
	v_or_b32_e32 v37, s12, v37
	s_movk_i32 s3, 0xb0
	v_mov_b32_e32 v148, v149
	s_add_i32 s16, s16, 48
	v_mul_lo_u32 v37, v37, s3
	v_mov_b32_e32 v144, v148
	v_add_u32_e32 v168, s16, v37
	v_cmp_gt_i32_e64 s[8:9], s76, v24
	v_mov_b32_e32 v145, v149
	v_mov_b32_e32 v146, v150
	s_and_saveexec_b64 s[4:5], s[8:9]
	s_cbranch_execz .LBB0_29
	v_mov_b32_e32 v169, v149
	v_lshl_add_u64 v[38:39], v[168:169], 2, s[74:75]
	global_load_dwordx3 v[144:146], v[38:39], off

; #define TIDX tid_()
; template <bool ISM>
; __device__ void scan_item(const Params& p, int l, int item, unsigned char* lds) {
;     constexpr int NT = ISM ? 5 : 4;
;     constexpr float L2E = 1.4426950408889634f;
;     const int tid = TIDX, wid = __builtin_amdgcn_readfirstlane(tid >> 6), lane = tid & 63, fr = lane & 15, fq = lane >> 4;
;     const int trq = fr >> 2, trp = fr & 3;
;     const int sl = ISM ? (item & 3) : 0, dir = ISM ? ((item >> 2) & 1) : (item & 1), h = ISM ? ((item >> 3) & 7) : ((item >> 1) & 31), b = item >> 6;
;     const int qcol = ISM ? h * 128 : 2048 + 2560 + (h >> 3) * 128;
;     const int kcol = ISM ? 1024 + h * 128 : 2048 + 2048 + (h >> 3) * 128;
;     const int vcol = ISM ? 2048 + h * 256 + sl * 64 : 2048 + h * 64;
;     const int ocol = ISM ? h * 256 + sl * 64 : h * 64;
;     u16* const obase = dir ? (ISM ? p.HB : p.YB) : (ISM ? p.P : p.P + 8192);
;     const unsigned ostride = dir ? 2048u : (unsigned)PW;
;     u16* Ks = (u16*)(lds + LS_K); u16* Vs = (u16*)(lds + LS_V); u16* Vw = (u16*)(lds + LS_VW); u16* CT = (u16*)(lds + LS_CT);
;     float* F = (float*)(lds + LS_F);
;     float *f_c = F, *f_r = F + 128, *f_wi = F + 256, *f_ws = F + 384, *f_em = F + 512;
;     const unsigned ldsb = (unsigned)(size_t)(LAS unsigned char*)lds;
;     const unsigned trK = ldsb + LS_K + (unsigned)(((fq * 8 + trq) * LDK + 16 * wid + 4 * trp) * 2);
;     const unsigned trVw = ldsb + LS_VW + (unsigned)(((fq * 8 + trq) * LDV + 4 * trp) * 2);
;     const unsigned trV = ldsb + LS_V + (unsigned)(((fq * 4 + trq) * LDV + 4 * trp) * 2);
;     const float Dh = ISM ? 0.f : p.d_skip[l * 32 + h];
;     const u16* __restrict__ gQKX = p.QKX; const u16* __restrict__ gP = p.P; const float* __restrict__ gG2 = p.G2;
;     const int gcol = ISM ? (dir * 8 + h) * 3 : 48 + (dir * 32 + h) * 2;
;     __syncthreads();
;     for (int i = tid; i < 128 * 24; i += 512) { const int r = i / 24, cc = 64 + i % 24; Vs[r * LDV + cc] = (ISM && cc == 64) ? (u16)0x3F80 : (u16)0; Vw[r * LDV + cc] = 0; }
;     for (int i = tid; i < 80 * LDK; i += 512) CT[i] = 0;
;     f32x4 st[NT];
; #pragma unroll
;     for (int m = 0; m < NT; ++m) st[m] = (f32x4){0.f, 0.f, 0.f, 0.f};
;     float m_prev = 0.f;
;     unsigned qo, ko[4], vo[2], go, ge, oo[4];
;     bf16x8 qf[4]; u32x4 kr[4]; u32x4 vr[2]; f32x3 gv = {0.f, 0.f, 0.f}; float e0 = 0.f, e1 = 0.f;
;     ...
;     SCAN_PTRS(0); SCAN_LOAD();
.LBB0_159:
	s_or_b64 exec, exec, s[4:5]
	s_lshl_b32 s3, s68, 2
	s_and_b32 s3, s3, 24
	s_and_b32 s4, s68, 32
	s_or_b32 s3, s3, s4
	s_lshl_b32 s5, s69, 6
	s_lshr_b32 s6, s3, 3
	s_lshl_b32 s4, s3, 4
	s_lshl_b32 s3, s3, 5
	s_and_b32 s5, s5, 0xc0
	v_lshlrev_b32_e32 v1, 3, v20
	s_ashr_i32 s16, s8, 6
	s_cmp_lt_i32 s16, 4
	s_cbranch_scc1 .Lwid_keep_m
	s_sub_i32 s16, 11, s16
.Lwid_keep_m:
	s_and_b32 s10, s68, 1
	s_ashr_i32 s11, s68, 6
	s_or_b32 s12, s3, s5
	v_and_b32_e32 v33, 0x78, v1
	s_cmp_eq_u32 s10, 0
	v_or_b32_e32 v2, s4, v33
	v_ashrrev_i32_e32 v24, 4, v20
	s_cselect_b64 vcc, -1, 0
	v_or_b32_e32 v16, 0x400, v2
	v_sub_u32_e32 v2, 0xff, v24
	s_lshl_b32 s3, s11, 8
	v_cndmask_b32_e32 v2, v2, v24, vcc
	v_add_u32_e32 v2, s3, v2
	v_or_b32_e32 v32, s4, v23
	v_mad_u64_u32 v[158:159], s[4:5], v2, s92, v[16:17]
	v_add_u32_e32 v2, 0x200, v20
	v_ashrrev_i32_e32 v25, 4, v2
	v_sub_u32_e32 v3, 0xff, v25
	v_cndmask_b32_e32 v3, v3, v25, vcc
	v_add_u32_e32 v3, s3, v3
	v_mad_u64_u32 v[160:161], s[4:5], v3, s92, v[16:17]
	v_add_u32_e32 v3, 0x400, v20
	v_ashrrev_i32_e32 v26, 4, v3
	v_sub_u32_e32 v3, 0xff, v26
	v_and_b32_e32 v34, 56, v1
	s_lshl_b32 s9, s16, 4
	v_cndmask_b32_e32 v3, v3, v26, vcc
	v_or_b32_e32 v1, s12, v34
	v_ashrrev_i32_e32 v21, 3, v20
	v_or_b32_e32 v31, s9, v19
	v_add_u32_e32 v3, s3, v3
	v_or_b32_e32 v18, 0x800, v1
	v_sub_u32_e32 v1, 0xff, v21
	v_sub_u32_e32 v0, 0xff, v31
	v_mad_u64_u32 v[162:163], s[4:5], v3, s92, v[16:17]
	v_add_u32_e32 v3, 0x600, v20
	v_cndmask_b32_e32 v1, v1, v21, vcc
	v_cndmask_b32_e32 v0, v0, v31, vcc
	v_ashrrev_i32_e32 v27, 4, v3
	v_add_u32_e32 v1, s3, v1
	s_movk_i32 s7, 0x3400
	v_ashrrev_i32_e32 v22, 3, v2
	v_add_u32_e32 v0, s3, v0
	v_sub_u32_e32 v3, 0xff, v27
	v_mad_u64_u32 v[168:169], s[4:5], v1, s7, v[18:19]
	v_sub_u32_e32 v1, 0xff, v22
	v_cndmask_b32_e32 v3, v3, v27, vcc
	v_mul_lo_u32 v0, v0, s92
	v_cndmask_b32_e32 v1, v1, v22, vcc
	v_add_u32_e32 v3, s3, v3
	v_add_u32_e32 v1, s3, v1
	v_or_b32_e32 v166, v0, v32
	v_mov_b32_e32 v167, v149
	v_mad_u64_u32 v[164:165], s[4:5], v3, s92, v[16:17]
	v_mad_u64_u32 v[170:171], s[4:5], v1, s7, v[18:19]
	v_lshl_add_u64 v[0:1], v[166:167], 1, s[72:73]
	global_load_dwordx4 v[72:75], v[0:1], off
	global_load_dwordx4 v[68:71], v[0:1], off offset:64
	global_load_dwordx4 v[64:67], v[0:1], off offset:128
	global_load_dwordx4 v[60:63], v[0:1], off offset:192
	v_mov_b32_e32 v159, v149
	v_mov_b32_e32 v161, v149
	v_mov_b32_e32 v163, v149
	v_mov_b32_e32 v165, v149
	v_mov_b32_e32 v169, v149
	v_lshl_add_u64 v[0:1], v[158:159], 1, s[72:73]
	v_lshl_add_u64 v[4:5], v[160:161], 1, s[72:73]
	v_lshl_add_u64 v[8:9], v[162:163], 1, s[72:73]
	v_lshl_add_u64 v[12:13], v[164:165], 1, s[72:73]
	v_lshl_add_u64 v[36:37], v[168:169], 1, s[70:71]
	v_mov_b32_e32 v171, v149
	global_load_dwordx4 v[0:3], v[0:1], off
	s_nop 0
	global_load_dwordx4 v[4:7], v[4:5], off
	s_nop 0
	global_load_dwordx4 v[8:11], v[8:9], off
	s_nop 0
	global_load_dwordx4 v[12:15], v[12:13], off
	v_lshl_add_u64 v[38:39], v[170:171], 1, s[70:71]
	global_load_dwordx4 v[80:83], v[36:37], off
	global_load_dwordx4 v[76:79], v[38:39], off
	v_and_b32_e32 v35, 0x7f, v20
	v_bitop3_b32 v36, v20, s2, v217 bitop3:0x6c
	s_lshl_b32 s4, s10, 3
	v_cndmask_b32_e32 v36, v36, v35, vcc
	s_or_b32 s67, s6, s4
	v_or_b32_e32 v36, s3, v36
	s_movk_i32 s4, 0xb0
	v_mov_b32_e32 v150, v149
	s_mul_i32 s67, s67, 3
	v_mul_lo_u32 v36, v36, s4
	v_mov_b32_e32 v148, v149
	v_mov_b32_e32 v152, v150
	v_add_u32_e32 v172, s67, v36
	v_cmp_gt_i32_e64 s[6:7], s76, v20
	v_mov_b32_e32 v151, v149
	v_mov_b32_e32 v150, v148
	s_and_saveexec_b64 s[4:5], s[6:7]
	s_cbranch_execz .LBB0_161
	v_mov_b32_e32 v173, v149
	v_lshl_add_u64 v[36:37], v[172:173], 2, s[74:75]
	global_load_dwordx3 v[150:152], v[36:37], off

; #define LAS __attribute__((address_space(3)))
; #define KOUT() ((float*)kload<20>())
; #define KWS() ((unsigned char*)kload<21>())
; #define BIDX bid_()
; #define GDIM gdim_()
; __global__ __launch_bounds__(512, 2) void mega(KArgs ka, int ph_lo, int ph_hi) {
;     ...
;                 if (l >= 1 && l < DEPTH) {
;                     q.w_in = KIN(6); q.w_out = KIN(17); q.wt_in = (u16*)(ws + OFF_W); q.wt_out = (u16*)(ws + OFF_W + SZ_WTIN1);
;                     weight_tiles(q, (float*)shm, l);
;                 }
;     ...
;             } else {
;                 unsigned char* ws = KWS(); float* outp = KOUT();
;                 const float* xin = KIN(0); const float* cin = KIN(2);
;                 float* rc = (float*)(ws + OFF_RC);
;                 const int roff = (l == DEPTH - 1) ? CTXROWS : 0;
;                 pg8::Gemm g{(const u16*)(ws + OFF_P) + (size_t)roff * PW + 9216, (const u16*)(ws + OFF_W + (size_t)l * SZ_WL + SZ_WTIN1), MROWS - roff, 2048, 4096, PW};
;                 pg8::StaticOrder S; S.init(MROWS - roff, 2048, GDIM, BIDX);
;                 EpiG2 E{l == 0 ? xin : outp, l == 0 ? cin : rc, outp, rc, (const float*)(ws + OFF_MOD) + (size_t)l * 3 * 6144, roff};
;                 pg8::gemm_phase<EpiG2>((LAS unsigned char*)shm, g, S, E);
.LBB0_340:
	s_mov_b64 s[56:57], 0
	v_readlane_b32 s3, v254, 18
	s_cmp_lg_u32 s3, 6
	s_cbranch_scc1 .LBB0_341
	s_cmp_lt_u32 s2, 16
	s_cbranch_scc1 .LBB0_341
	s_waitcnt lgkmcnt(0)
	s_mov_b32 s101, s2
	s_mov_b32 s100, 1
	s_add_i32 s2, s2, -16
	s_add_i32 s59, s59, -16
	s_load_dwordx2 s[4:5], s[0:1], 0xa8
	s_waitcnt lgkmcnt(0)
	s_branch .Lwt_entry

; #define TIDX tid_()
; #define BIDX bid_()
; #define GDIM gdim_()
; __device__ __forceinline__ TrTile tr_tile(const Params& p, int t) {
;     constexpr int T_IN = (NPAD / 64) * 16, T_OUT = 32 * 32;
;     const int l = t / (T_IN + T_OUT), r = t % (T_IN + T_OUT);
;     TrTile o;
;     if (r < T_IN) { o.src = p.w_in + (size_t)l * 2048 * NIN; o.dst = p.wt_in + (size_t)l * (SZ_WL / 2); o.Nsrc = NIN; o.K = 2048; o.n0 = (r >> 4) * 64; o.k0 = (r & 15) * 128; o.perm = 1; }
;     else { const int r2 = r - T_IN; o.src = p.w_out + (size_t)l * 4096 * 2048; o.dst = p.wt_out + (size_t)l * (SZ_WL / 2); o.Nsrc = 2048; o.K = 4096; o.n0 = (r2 >> 5) * 64; o.k0 = (r2 & 31) * 128; o.perm = 0; }
; __device__ void weight_tiles(const Params& p, float* sf, int l) {
;     constexpr int T_L = (NPAD / 64) * 16 + 32 * 32;
;     const int tid = TIDX, gd = GDIM;
;     const int t_end = (l + 1) * T_L;
;     int t = l * T_L + BIDX;
;     float v[16];
;     __syncthreads();
;     if (t < t_end) { const TrTile c0 = tr_tile(p, t); tr_load(c0, v, tid); }
.LBB0_354:
	s_or_b64 exec, exec, s[14:15]
	s_branch .LBB0_437
.Lwt_entry:
	s_load_dwordx2 s[6:7], s[0:1], 48
	s_waitcnt lgkmcnt(0)
	s_waitcnt vmcnt(0)
	v_mov_b32_e32 v2, v206
	s_mov_b32 s3, s59
	s_mov_b32 s12, s2
	s_load_dwordx2 s[8:9], s[0:1], 0x88
	s_waitcnt lgkmcnt(0)
	s_add_i32 s24, s12, 0x1140
	s_cmpk_lt_i32 s12, 0x1140
	s_cselect_b64 s[10:11], -1, 0
	s_cmpk_gt_i32 s12, 0x113f
	s_barrier
	s_cbranch_scc1 .LBB0_392
	s_mul_hi_i32 s12, s24, 0x76b981db
	s_lshr_b32 s13, s12, 31
	s_ashr_i32 s12, s12, 11
	s_add_i32 s12, s12, s13
	s_mul_i32 s13, s12, 0x1140
	s_sub_i32 s20, s24, s13
	s_cmpk_gt_i32 s20, 0xd3f
	s_cselect_b64 s[16:17], -1, 0
	s_ashr_i32 s13, s12, 31
	s_mov_b64 s[18:19], -1
	s_and_b64 vcc, exec, s[16:17]
	s_cbranch_vccnz .LBB0_358
	s_mul_i32 s14, s12, 0x68c0000
	s_mul_hi_i32 s15, s12, 0x68c0000
	s_add_u32 s14, s6, s14
	s_addc_u32 s15, s7, s15
	s_lshl_b32 s18, s20, 2
	s_and_b32 s21, s18, 0xffffffc0
	s_mov_b64 s[18:19], 0

; #define KWS() ((unsigned char*)kload<21>())
; #define GDIM gdim_()
; __global__ __launch_bounds__(512, 2) void mega(KArgs ka, int ph_lo, int ph_hi) {
;     ...
;         if (ph + 1 < ph_hi) {
;             if (ph_hi > N_PHASES) { grid.sync(); acquire_workgroup(); }
;             grid_barrier((unsigned*)(KWS() + OFF_BAR), (unsigned)(ph - ph_lo + 1) * (unsigned)GDIM);
;         }
.LBB0_437:
	s_cmp_eq_u32 s100, 0
	s_cbranch_scc1 .Lwt_norestore
	s_mov_b32 s2, s101
	s_load_dword s59, s[0:1], 0xb8
	s_mov_b32 s100, 0
	s_waitcnt lgkmcnt(0)

; __global__ __launch_bounds__(512, 2) void mega(KArgs ka, int ph_lo, int ph_hi) {
	.amdhsa_kernel _Z4mega5KArgsii
		.amdhsa_group_segment_fixed_size 0
		.amdhsa_private_segment_fixed_size 0
		.amdhsa_kernarg_size 440
		.amdhsa_user_sgpr_count 2
		.amdhsa_user_sgpr_dispatch_ptr 0
		.amdhsa_user_sgpr_queue_ptr 0
		.amdhsa_user_sgpr_kernarg_segment_ptr 1
		.amdhsa_user_sgpr_dispatch_id 0
		.amdhsa_user_sgpr_kernarg_preload_length 0
		.amdhsa_user_sgpr_kernarg_preload_offset 0
		.amdhsa_user_sgpr_private_segment_size 0
		.amdhsa_uses_dynamic_stack 0
		.amdhsa_enable_private_segment 0
		.amdhsa_system_sgpr_workgroup_id_x 1
		.amdhsa_system_sgpr_workgroup_id_y 0
		.amdhsa_system_sgpr_workgroup_id_z 0
		.amdhsa_system_sgpr_workgroup_info 0
		.amdhsa_system_vgpr_workitem_id 2
		.amdhsa_next_free_vgpr 255
		.amdhsa_next_free_sgpr 102
		.amdhsa_accum_offset 256
		.amdhsa_reserve_vcc 1
		.amdhsa_float_round_mode_32 0
		.amdhsa_float_round_mode_16_64 0
		.amdhsa_float_denorm_mode_32 3
		.amdhsa_float_denorm_mode_16_64 3
		.amdhsa_dx10_clamp 1
		.amdhsa_ieee_mode 1
		.amdhsa_fp16_overflow 0
		.amdhsa_tg_split 0
		.amdhsa_exception_fp_ieee_invalid_op 0
		.amdhsa_exception_fp_denorm_src 0
		.amdhsa_exception_fp_ieee_div_zero 0
		.amdhsa_exception_fp_ieee_overflow 0
		.amdhsa_exception_fp_ieee_underflow 0
		.amdhsa_exception_fp_ieee_inexact 0
		.amdhsa_exception_int_div_zero 0
	.end_amdhsa_kernel

; __global__ __launch_bounds__(512, 2) void mega(KArgs ka, int ph_lo, int ph_hi) {
amdhsa.kernels:
  - .agpr_count:     0
    .args:
      - .offset:         0
        .size:           176
        .value_kind:     by_value
      - .offset:         176
        .size:           4
        .value_kind:     by_value
      - .offset:         180
        .size:           4
        .value_kind:     by_value
      - .offset:         184
        .size:           4
        .value_kind:     hidden_block_count_x
      - .offset:         188
        .size:           4
        .value_kind:     hidden_block_count_y
      - .offset:         192
        .size:           4
        .value_kind:     hidden_block_count_z
      - .offset:         196
        .size:           2
        .value_kind:     hidden_group_size_x
      - .offset:         198
        .size:           2
        .value_kind:     hidden_group_size_y
      - .offset:         200
        .size:           2
        .value_kind:     hidden_group_size_z
      - .offset:         202
        .size:           2
        .value_kind:     hidden_remainder_x
      - .offset:         204
        .size:           2
        .value_kind:     hidden_remainder_y
      - .offset:         206
        .size:           2
        .value_kind:     hidden_remainder_z
      - .offset:         224
        .size:           8
        .value_kind:     hidden_global_offset_x
      - .offset:         232
        .size:           8
        .value_kind:     hidden_global_offset_y
      - .offset:         240
        .size:           8
        .value_kind:     hidden_global_offset_z
      - .offset:         248
        .size:           2
        .value_kind:     hidden_grid_dims
      - .offset:         272
        .size:           8
        .value_kind:     hidden_multigrid_sync_arg
      - .offset:         304
        .size:           4
        .value_kind:     hidden_dynamic_lds_size
    .group_segment_fixed_size: 0
    .kernarg_segment_align: 8
    .kernarg_segment_size: 440
    .language:       OpenCL C
    .language_version:
      - 2
      - 0
    .max_flat_workgroup_size: 512
    .name:           _Z4mega5KArgsii
    .private_segment_fixed_size: 0
    .sgpr_count:     108
    .sgpr_spill_count: 39
    .symbol:         _Z4mega5KArgsii.kd
    .uniform_work_group_size: 1
    .uses_dynamic_stack: false
    .vgpr_count:     255
    .vgpr_spill_count: 0
    .wavefront_size: 64
